# attention k-loop: next tile K/V global loads issued right after the top barrier
# speedup vs baseline: 1.2345x; 1.0042x over previous
.LBB0_117:
	s_waitcnt vmcnt(0)
	ds_write_b128 v158, v[100:103]
	ds_write_b128 v158, v[104:107] offset:4352
	ds_write_b128 v158, v[96:99] offset:8704
	ds_write_b128 v158, v[88:91] offset:13056
	ds_write_b128 v151, v[108:111] offset:17408
	ds_write_b128 v151, v[92:95] offset:22016
	ds_write_b128 v151, v[84:87] offset:26624
	ds_write_b128 v151, v[80:83] offset:31232
	s_waitcnt lgkmcnt(0)
	s_barrier
	v_lshl_add_u64 v[80:81], s[96:97], 0, v[156:157]
	s_mov_b32 s0, 0x1feb6000
	v_add_co_u32_e32 v84, vcc, s0, v80
	s_nop 1
	v_addc_co_u32_e32 v85, vcc, 0, v81, vcc
	s_mov_b32 s0, 0x1feba000
	global_load_dwordx4 v[100:103], v[84:85], off offset:256
	v_add_co_u32_e32 v84, vcc, s0, v80
	s_nop 1
	v_addc_co_u32_e32 v85, vcc, 0, v81, vcc
	s_mov_b32 s0, 0x1febe000
	global_load_dwordx4 v[104:107], v[84:85], off offset:256
	v_add_co_u32_e32 v84, vcc, s0, v80
	s_nop 1
	v_addc_co_u32_e32 v85, vcc, 0, v81, vcc
	s_mov_b32 s0, 0x1fec2000
	v_add_co_u32_e32 v80, vcc, s0, v80
	s_nop 1
	v_lshl_add_u64 v[82:83], s[96:97], 0, v[154:155]
	v_addc_co_u32_e32 v81, vcc, 0, v81, vcc
	s_mov_b32 s0, 0x20726000
	global_load_dwordx4 v[96:99], v[84:85], off offset:256
	global_load_dwordx4 v[88:91], v[80:81], off offset:256
	v_add_co_u32_e32 v80, vcc, s0, v82
	s_nop 1
	v_addc_co_u32_e32 v81, vcc, 0, v83, vcc
	s_mov_b32 s0, 0x2072a000
	global_load_dwordx4 v[108:111], v[80:81], off offset:384
	v_add_co_u32_e32 v80, vcc, s0, v82
	s_nop 1
	v_addc_co_u32_e32 v81, vcc, 0, v83, vcc
	s_mov_b32 s0, 0x2072e000
	global_load_dwordx4 v[92:95], v[80:81], off offset:384
	v_add_co_u32_e32 v80, vcc, s0, v82
	s_nop 1
	s_mov_b32 s0, 0x20732000
	v_addc_co_u32_e32 v81, vcc, 0, v83, vcc
	global_load_dwordx4 v[84:87], v[80:81], off offset:384
	v_add_co_u32_e32 v80, vcc, s0, v82
	s_nop 1
	v_addc_co_u32_e32 v81, vcc, 0, v83, vcc
	global_load_dwordx4 v[80:83], v[80:81], off offset:384
	ds_read_b128 v[112:115], v147
	ds_read_b128 v[116:119], v147 offset:64
	s_nop 0
	s_nop 0
	s_nop 0
	s_waitcnt lgkmcnt(1)
	v_mfma_f32_16x16x32_bf16 v[112:115], v[112:115], v[76:79], 0
	ds_read_b128 v[120:123], v147 offset:192
	s_nop 0
	s_waitcnt lgkmcnt(1)
	v_mfma_f32_16x16x32_bf16 v[112:115], v[116:119], v[72:75], v[112:115]
	ds_read_b128 v[116:119], v147 offset:128
	s_nop 0
	s_nop 0
	s_nop 0
	s_waitcnt lgkmcnt(0)
	v_mfma_f32_16x16x32_bf16 v[116:119], v[116:119], v[68:71], 0
	ds_read_b128 v[124:127], v147 offset:4416
	s_nop 0
	v_mul_f32_e32 v112, 0x3fb8aa3b, v112
	v_exp_f32_e32 v132, v112
	v_mfma_f32_16x16x32_bf16 v[120:123], v[120:123], v[64:67], v[116:119]
	v_mul_f32_e32 v112, 0x3fb8aa3b, v113
	v_exp_f32_e32 v134, v112
	v_mul_f32_e32 v112, 0x3fb8aa3b, v114
	ds_read_b128 v[116:119], v147 offset:4352
	s_waitcnt lgkmcnt(0)
	v_mfma_f32_16x16x32_bf16 v[116:119], v[116:119], v[76:79], 0
	ds_read_b128 v[160:163], v147 offset:4544
	s_nop 0
	v_mul_f32_e32 v120, 0x3fb8aa3b, v120
	v_exp_f32_e32 v133, v120
	v_mfma_f32_16x16x32_bf16 v[116:119], v[124:127], v[72:75], v[116:119]
	ds_read_b128 v[124:127], v147 offset:4480
	v_mul_f32_e32 v120, 0x3fb8aa3b, v121
	v_exp_f32_e32 v135, v120
	s_waitcnt lgkmcnt(0)
	v_mfma_f32_16x16x32_bf16 v[124:127], v[124:127], v[68:71], 0
	ds_read_b128 v[164:167], v147 offset:8768
	v_mul_f32_e32 v120, 0x3fb8aa3b, v122
	v_exp_f32_e32 v136, v112
	v_mfma_f32_16x16x32_bf16 v[124:127], v[160:163], v[64:67], v[124:127]
	ds_read_b128 v[160:163], v147 offset:8704
	v_mul_f32_e32 v112, 0x3fb8aa3b, v115
	ds_read_b128 v[168:171], v147 offset:8896
	s_waitcnt lgkmcnt(1)
	v_mfma_f32_16x16x32_bf16 v[160:163], v[160:163], v[76:79], 0
	v_exp_f32_e32 v137, v120
	v_mul_f32_e32 v120, 0x3fb8aa3b, v123
	v_exp_f32_e32 v138, v112
	v_mfma_f32_16x16x32_bf16 v[160:163], v[164:167], v[72:75], v[160:163]
	ds_read_b128 v[164:167], v147 offset:8832
	ds_read_b128 v[172:175], v147 offset:13120
	v_mul_f32_e32 v112, 0x3fb8aa3b, v116
	s_waitcnt lgkmcnt(1)
	v_mfma_f32_16x16x32_bf16 v[164:167], v[164:167], v[68:71], 0
	v_exp_f32_e32 v139, v120
	v_mul_f32_e32 v120, 0x3fb8aa3b, v124
	v_exp_f32_e32 v140, v112
	v_mfma_f32_16x16x32_bf16 v[164:167], v[168:171], v[64:67], v[164:167]
	ds_read_b128 v[168:171], v147 offset:13056
	ds_read_b128 v[176:179], v147 offset:13248
	v_mul_f32_e32 v112, 0x3fb8aa3b, v117
	s_waitcnt lgkmcnt(1)
	v_mfma_f32_16x16x32_bf16 v[168:171], v[168:171], v[76:79], 0
	v_exp_f32_e32 v141, v120
	v_mul_f32_e32 v120, 0x3fb8aa3b, v125
	v_exp_f32_e32 v142, v112
	v_mfma_f32_16x16x32_bf16 v[168:171], v[172:175], v[72:75], v[168:171]
	ds_read_b128 v[172:175], v147 offset:13184
	v_mul_f32_e32 v112, 0x3fb8aa3b, v118
	v_exp_f32_e32 v143, v120
	s_waitcnt lgkmcnt(0)
	v_mfma_f32_16x16x32_bf16 v[172:175], v[172:175], v[68:71], 0
	v_add_f32_e64 v120, v132, 0
	v_add_f32_e64 v121, v133, 0
	v_mul_f32_e32 v122, 0x3fb8aa3b, v126
	v_pk_add_f32 v[120:121], v[134:135], v[120:121]
	v_mfma_f32_16x16x32_bf16 v[172:175], v[176:179], v[64:67], v[172:175]
	v_exp_f32_e32 v176, v112
	v_mul_f32_e32 v112, 0x3fb8aa3b, v119
	v_exp_f32_e32 v177, v122
	v_mul_f32_e32 v122, 0x3fb8aa3b, v127
	v_exp_f32_e32 v178, v112
	v_mul_f32_e32 v112, 0x3fb8aa3b, v160
	v_pk_add_f32 v[120:121], v[136:137], v[120:121]
	v_exp_f32_e32 v179, v122
	v_mul_f32_e32 v122, 0x3fb8aa3b, v164
	v_exp_f32_e32 v160, v112
	v_mul_f32_e32 v112, 0x3fb8aa3b, v161
	v_pk_add_f32 v[120:121], v[138:139], v[120:121]
	v_exp_f32_e32 v161, v122
	v_mul_f32_e32 v122, 0x3fb8aa3b, v165
	v_exp_f32_e32 v180, v112
	v_mul_f32_e32 v112, 0x3fb8aa3b, v162
	v_pk_add_f32 v[120:121], v[120:121], v[140:141]
	v_exp_f32_e32 v181, v122
	v_mul_f32_e32 v122, 0x3fb8aa3b, v166
	v_exp_f32_e32 v162, v112
	v_mul_f32_e32 v112, 0x3fb8aa3b, v163
	v_pk_add_f32 v[120:121], v[142:143], v[120:121]
	v_exp_f32_e32 v163, v122
	v_mul_f32_e32 v122, 0x3fb8aa3b, v167
	v_exp_f32_e32 v182, v112
	v_exp_f32_e32 v183, v122
	v_pk_add_f32 v[120:121], v[176:177], v[120:121]
	v_mul_f32_e32 v112, 0x3fb8aa3b, v168
	v_pk_add_f32 v[120:121], v[178:179], v[120:121]
	v_mul_f32_e32 v122, 0x3fb8aa3b, v172
	v_pk_add_f32 v[120:121], v[120:121], v[160:161]
	v_cvt_pk_bf16_f32 v124, v161, v181
	v_pk_add_f32 v[120:121], v[180:181], v[120:121]
	v_add_u32_e32 v161, 0x4000, v159
	v_exp_f32_e32 v168, v112
	v_mul_f32_e32 v112, 0x3fb8aa3b, v169
	v_cvt_pk_bf16_f32 v113, v162, v182
	v_exp_f32_e32 v169, v122
	v_mul_f32_e32 v122, 0x3fb8aa3b, v173
	v_pk_add_f32 v[120:121], v[162:163], v[120:121]
	v_cvt_pk_bf16_f32 v125, v163, v183
	ds_read2_b64 v[162:165], v161 offset0:128 offset1:132
	v_exp_f32_e32 v184, v112
	v_mul_f32_e32 v112, 0x3fb8aa3b, v170
	v_exp_f32_e32 v185, v122
	v_mul_f32_e32 v122, 0x3fb8aa3b, v174
	v_exp_f32_e32 v170, v112
	v_mul_f32_e32 v112, 0x3fb8aa3b, v171
	v_exp_f32_e32 v171, v122
	v_mul_f32_e32 v122, 0x3fb8aa3b, v175
	v_exp_f32_e32 v186, v112
	v_exp_f32_e32 v187, v122
	v_pk_add_f32 v[120:121], v[182:183], v[120:121]
	v_cvt_pk_bf16_f32 v116, v132, v134
	v_pk_add_f32 v[120:121], v[120:121], v[168:169]
	v_cvt_pk_bf16_f32 v117, v136, v138
	v_pk_add_f32 v[120:121], v[184:185], v[120:121]
	v_cvt_pk_bf16_f32 v118, v140, v142
	v_pk_add_f32 v[120:121], v[170:171], v[120:121]
	v_cvt_pk_bf16_f32 v119, v176, v178
	v_pk_add_f32 v[120:121], v[186:187], v[120:121]
	v_cvt_pk_bf16_f32 v122, v141, v143
	v_pk_add_f32 v[152:153], v[152:153], v[120:121]
	v_cvt_pk_bf16_f32 v120, v133, v135
	v_cvt_pk_bf16_f32 v121, v137, v139
	v_cvt_pk_bf16_f32 v123, v177, v179
	s_waitcnt lgkmcnt(0)
	v_mfma_f32_16x16x32_bf16 v[60:63], v[162:165], v[116:119], v[60:63]
	v_cvt_pk_bf16_f32 v112, v160, v180
	v_cvt_pk_bf16_f32 v114, v168, v184
	v_cvt_pk_bf16_f32 v115, v170, v186
	v_mfma_f32_16x16x32_bf16 v[56:59], v[162:165], v[120:123], v[56:59]
	ds_read2_b64 v[162:165], v161 offset0:136 offset1:140
	v_cvt_pk_bf16_f32 v126, v169, v185
	v_cvt_pk_bf16_f32 v127, v171, v187
	v_add_u32_e32 v160, 0x4800, v159
	s_waitcnt lgkmcnt(0)
	v_mfma_f32_16x16x32_bf16 v[60:63], v[162:165], v[112:115], v[60:63]
	s_nop 0
	s_nop 0
	v_mfma_f32_16x16x32_bf16 v[56:59], v[162:165], v[124:127], v[56:59]
	ds_read2_b64 v[162:165], v160 offset0:160 offset1:164
	s_nop 0
	s_nop 0
	s_waitcnt lgkmcnt(0)
	v_mfma_f32_16x16x32_bf16 v[52:55], v[162:165], v[116:119], v[52:55]
	s_nop 0
	s_nop 0
	v_mfma_f32_16x16x32_bf16 v[44:47], v[162:165], v[120:123], v[44:47]
	ds_read2_b64 v[162:165], v160 offset0:168 offset1:172
	s_nop 0
	s_waitcnt lgkmcnt(0)
	v_mfma_f32_16x16x32_bf16 v[52:55], v[162:165], v[112:115], v[52:55]
	s_nop 0
	s_nop 0
	v_mfma_f32_16x16x32_bf16 v[44:47], v[162:165], v[124:127], v[44:47]
	v_add_u32_e32 v162, 0x5000, v159
	ds_read2_b64 v[164:167], v162 offset0:192 offset1:196
	v_add_u32_e32 v163, 0x5800, v159
	s_waitcnt lgkmcnt(0)
	v_mfma_f32_16x16x32_bf16 v[48:51], v[164:167], v[116:119], v[48:51]
	s_nop 0
	s_nop 0
	s_nop 0
	v_mfma_f32_16x16x32_bf16 v[36:39], v[164:167], v[120:123], v[36:39]
	ds_read2_b64 v[164:167], v162 offset0:200 offset1:204
	s_nop 0
	s_waitcnt lgkmcnt(0)
	v_mfma_f32_16x16x32_bf16 v[48:51], v[164:167], v[112:115], v[48:51]
	s_nop 0
	s_nop 0
	v_mfma_f32_16x16x32_bf16 v[36:39], v[164:167], v[124:127], v[36:39]
	ds_read2_b64 v[164:167], v163 offset0:224 offset1:228
	s_nop 0
	s_nop 0
	s_waitcnt lgkmcnt(0)
	v_mfma_f32_16x16x32_bf16 v[40:43], v[164:167], v[116:119], v[40:43]
	s_nop 0
	s_nop 0
	v_mfma_f32_16x16x32_bf16 v[28:31], v[164:167], v[120:123], v[28:31]
	ds_read2_b64 v[164:167], v163 offset0:232 offset1:236
	s_nop 0
	s_nop 0
	s_nop 0
	s_nop 0
	s_nop 0
	s_nop 0
	s_nop 0
	s_waitcnt lgkmcnt(0)
	v_mfma_f32_16x16x32_bf16 v[40:43], v[164:167], v[112:115], v[40:43]
	s_nop 0
	s_nop 0
	v_mfma_f32_16x16x32_bf16 v[28:31], v[164:167], v[124:127], v[28:31]
	v_add_u32_e32 v164, 0x6800, v159
	ds_read2_b64 v[166:169], v164 offset1:4
	v_add_u32_e32 v165, 0x7000, v159
	s_waitcnt lgkmcnt(0)
	v_mfma_f32_16x16x32_bf16 v[32:35], v[166:169], v[116:119], v[32:35]
	s_add_i32 s29, s29, -1
	v_lshl_add_u64 v[154:155], v[154:155], 0, s[4:5]
	v_lshl_add_u64 v[156:157], v[156:157], 0, s[6:7]
	v_mfma_f32_16x16x32_bf16 v[20:23], v[166:169], v[120:123], v[20:23]
	ds_read2_b64 v[166:169], v164 offset0:8 offset1:12
	s_cmp_lg_u32 s29, 0
	s_waitcnt lgkmcnt(0)
	v_mfma_f32_16x16x32_bf16 v[32:35], v[166:169], v[112:115], v[32:35]
	v_mfma_f32_16x16x32_bf16 v[20:23], v[166:169], v[124:127], v[20:23]
	ds_read2_b64 v[166:169], v165 offset0:32 offset1:36
	s_waitcnt lgkmcnt(0)
	v_mfma_f32_16x16x32_bf16 v[24:27], v[166:169], v[116:119], v[24:27]
	v_mfma_f32_16x16x32_bf16 v[12:15], v[166:169], v[120:123], v[12:15]
	ds_read2_b64 v[166:169], v165 offset0:40 offset1:44
	s_waitcnt lgkmcnt(0)
	v_mfma_f32_16x16x32_bf16 v[24:27], v[166:169], v[112:115], v[24:27]
	v_mfma_f32_16x16x32_bf16 v[12:15], v[166:169], v[124:127], v[12:15]
	v_add_u32_e32 v166, 0x7800, v159
	ds_read2_b64 v[168:171], v166 offset0:64 offset1:68
	v_add_u32_e32 v167, 0x8000, v159
	s_waitcnt lgkmcnt(0)
	v_mfma_f32_16x16x32_bf16 v[16:19], v[168:171], v[116:119], v[16:19]
	v_mfma_f32_16x16x32_bf16 v[4:7], v[168:171], v[120:123], v[4:7]
	ds_read2_b64 v[168:171], v166 offset0:72 offset1:76
	s_waitcnt lgkmcnt(0)
	v_mfma_f32_16x16x32_bf16 v[16:19], v[168:171], v[112:115], v[16:19]
	v_mfma_f32_16x16x32_bf16 v[4:7], v[168:171], v[124:127], v[4:7]
	ds_read2_b64 v[168:171], v167 offset0:96 offset1:100
	s_waitcnt lgkmcnt(0)
	v_mfma_f32_16x16x32_bf16 v[8:11], v[168:171], v[116:119], v[8:11]
	ds_read2_b64 v[116:119], v167 offset0:104 offset1:108
	s_waitcnt lgkmcnt(0)
	s_barrier
	v_mfma_f32_16x16x32_bf16 v[0:3], v[168:171], v[120:123], v[0:3]
	v_mfma_f32_16x16x32_bf16 v[8:11], v[116:119], v[112:115], v[8:11]
	v_mfma_f32_16x16x32_bf16 v[0:3], v[116:119], v[124:127], v[0:3]
	s_cbranch_scc1 .LBB0_117
	s_waitcnt vmcnt(7)
	ds_write_b128 v158, v[100:103]
	s_waitcnt vmcnt(6)
	ds_write_b128 v158, v[104:107] offset:4352
	s_waitcnt vmcnt(5)
	ds_write_b128 v158, v[96:99] offset:8704
	s_waitcnt vmcnt(4)
	ds_write_b128 v158, v[88:91] offset:13056
	s_waitcnt vmcnt(3)
	ds_write_b128 v151, v[108:111] offset:17408
	s_waitcnt vmcnt(2)
	ds_write_b128 v151, v[92:95] offset:22016
	s_waitcnt vmcnt(1)
	ds_write_b128 v151, v[84:87] offset:26624
	s_waitcnt vmcnt(0)
	ds_write_b128 v151, v[80:83] offset:31232
	s_waitcnt lgkmcnt(0)
	s_barrier
	ds_read_b128 v[80:83], v147
	ds_read_b128 v[84:87], v147 offset:64
	s_lshl_b32 s92, s28, 1
	s_waitcnt lgkmcnt(1)
	v_mfma_f32_16x16x32_bf16 v[80:83], v[80:83], v[76:79], 0
	ds_read_b128 v[88:91], v147 offset:192
	ds_read_b128 v[94:97], v147 offset:4416
	ds_read_b128 v[98:101], v147 offset:4544
	s_waitcnt lgkmcnt(3)
	v_mfma_f32_16x16x32_bf16 v[80:83], v[84:87], v[72:75], v[80:83]
	ds_read_b128 v[84:87], v147 offset:128
	ds_read_b128 v[102:105], v147 offset:8768
	ds_read_b128 v[106:109], v147 offset:8896
	s_waitcnt lgkmcnt(2)
	v_mfma_f32_16x16x32_bf16 v[84:87], v[84:87], v[68:71], 0
	v_mfma_f32_16x16x32_bf16 v[86:89], v[88:91], v[64:67], v[84:87]
	ds_read_b128 v[90:93], v147 offset:4352
	s_waitcnt lgkmcnt(0)
	v_mfma_f32_16x16x32_bf16 v[90:93], v[90:93], v[76:79], 0
	v_mfma_f32_16x16x32_bf16 v[90:93], v[94:97], v[72:75], v[90:93]
	ds_read_b128 v[94:97], v147 offset:4480
	s_waitcnt lgkmcnt(0)
	v_mfma_f32_16x16x32_bf16 v[94:97], v[94:97], v[68:71], 0
	v_mfma_f32_16x16x32_bf16 v[94:97], v[98:101], v[64:67], v[94:97]
	ds_read_b128 v[98:101], v147 offset:8704
	s_waitcnt lgkmcnt(0)
	v_mfma_f32_16x16x32_bf16 v[98:101], v[98:101], v[76:79], 0
	v_mfma_f32_16x16x32_bf16 v[98:101], v[102:105], v[72:75], v[98:101]
	ds_read_b128 v[102:105], v147 offset:8832
	s_waitcnt lgkmcnt(0)
	v_mfma_f32_16x16x32_bf16 v[102:105], v[102:105], v[68:71], 0
	v_mfma_f32_16x16x32_bf16 v[102:105], v[106:109], v[64:67], v[102:105]
	ds_read_b128 v[106:109], v147 offset:13056
	s_waitcnt lgkmcnt(0)
	v_mfma_f32_16x16x32_bf16 v[76:79], v[106:109], v[76:79], 0
	ds_read_b128 v[106:109], v147 offset:13120
	s_waitcnt lgkmcnt(0)
	v_mfma_f32_16x16x32_bf16 v[72:75], v[106:109], v[72:75], v[76:79]
	s_nop 4
	ds_read_b128 v[76:79], v147 offset:13184
	s_waitcnt lgkmcnt(0)
	v_mfma_f32_16x16x32_bf16 v[68:71], v[76:79], v[68:71], 0
	ds_read_b128 v[76:79], v147 offset:13248
	v_mov_b32_e32 v147, v131
	s_waitcnt lgkmcnt(0)
	v_mfma_f32_16x16x32_bf16 v[64:67], v[76:79], v[64:67], v[68:71]
	s_nop 3
	v_mul_f32_e32 v68, 0x3fb8aa3b, v80
	v_exp_f32_e32 v84, v68
	v_mul_f32_e32 v68, 0x3fb8aa3b, v81
	v_exp_f32_e32 v85, v68
	v_mul_f32_e32 v68, 0x3fb8aa3b, v82
	v_exp_f32_e32 v106, v68
	v_mul_f32_e32 v68, 0x3fb8aa3b, v83
	v_exp_f32_e32 v107, v68
	v_mul_f32_e32 v68, 0x3fb8aa3b, v90
	v_mul_f32_e32 v64, 0x3fb8aa3b, v64
	v_exp_f32_e32 v90, v68
	v_mul_f32_e32 v68, 0x3fb8aa3b, v91
	v_exp_f32_e32 v116, v64
	v_mul_f32_e32 v64, 0x3fb8aa3b, v65
	v_exp_f32_e32 v91, v68
	v_mul_f32_e32 v68, 0x3fb8aa3b, v92
	v_exp_f32_e32 v117, v64
	v_mul_f32_e32 v64, 0x3fb8aa3b, v66
	v_exp_f32_e32 v92, v68
	v_mul_f32_e32 v68, 0x3fb8aa3b, v93
	v_exp_f32_e32 v118, v64
	v_mul_f32_e32 v64, 0x3fb8aa3b, v67
	v_exp_f32_e32 v93, v68
	v_mul_f32_e32 v68, 0x3fb8aa3b, v98
	v_mul_f32_e32 v76, 0x3fb8aa3b, v86
	v_exp_f32_e32 v119, v64
	ds_read2_b64 v[64:67], v161 offset0:128 offset1:132
	v_exp_f32_e32 v98, v68
	v_mul_f32_e32 v68, 0x3fb8aa3b, v99
	v_exp_f32_e32 v112, v76
	v_mul_f32_e32 v76, 0x3fb8aa3b, v87
	v_exp_f32_e32 v99, v68
	v_mul_f32_e32 v68, 0x3fb8aa3b, v100
	v_exp_f32_e32 v113, v76
	v_mul_f32_e32 v76, 0x3fb8aa3b, v88
	v_exp_f32_e32 v100, v68
	v_mul_f32_e32 v68, 0x3fb8aa3b, v101
	v_exp_f32_e32 v114, v76
	v_mul_f32_e32 v76, 0x3fb8aa3b, v89
	v_exp_f32_e32 v101, v68
	v_mul_f32_e32 v68, 0x3fb8aa3b, v72
	v_exp_f32_e32 v115, v76
	v_mul_f32_e32 v76, 0x3fb8aa3b, v94
	ds_read2_b64 v[86:89], v161 offset0:136 offset1:140
	v_exp_f32_e32 v108, v68
	v_mul_f32_e32 v68, 0x3fb8aa3b, v73
	v_exp_f32_e32 v94, v76
	v_mul_f32_e32 v76, 0x3fb8aa3b, v95
	v_exp_f32_e32 v109, v68
	v_mul_f32_e32 v68, 0x3fb8aa3b, v74
	v_exp_f32_e32 v95, v76
	v_mul_f32_e32 v76, 0x3fb8aa3b, v96
	v_exp_f32_e32 v110, v68
	v_mul_f32_e32 v68, 0x3fb8aa3b, v75
	v_exp_f32_e32 v96, v76
	v_mul_f32_e32 v76, 0x3fb8aa3b, v97
	v_exp_f32_e32 v111, v68
	v_cvt_pk_bf16_f32 v72, v84, v85
	v_cvt_pk_bf16_f32 v73, v106, v107
	v_cvt_pk_bf16_f32 v74, v90, v91
	v_cvt_pk_bf16_f32 v75, v92, v93
	v_exp_f32_e32 v97, v76
	v_cvt_pk_bf16_f32 v68, v98, v99
	s_waitcnt lgkmcnt(1)
	v_mfma_f32_16x16x32_bf16 v[60:63], v[64:67], v[72:75], v[60:63]
	v_cvt_pk_bf16_f32 v69, v100, v101
	v_cvt_pk_bf16_f32 v70, v108, v109
	v_cvt_pk_bf16_f32 v71, v110, v111
	v_cvt_pk_bf16_f32 v80, v112, v113
	v_cvt_pk_bf16_f32 v81, v114, v115
	v_cvt_pk_bf16_f32 v82, v94, v95
	v_cvt_pk_bf16_f32 v83, v96, v97
	v_mul_f32_e32 v76, 0x3fb8aa3b, v102
	v_exp_f32_e32 v102, v76
	v_mfma_f32_16x16x32_bf16 v[64:67], v[64:67], v[80:83], v[56:59]
	v_mul_f32_e32 v76, 0x3fb8aa3b, v103
	v_exp_f32_e32 v103, v76
	v_mul_f32_e32 v76, 0x3fb8aa3b, v104
	s_waitcnt lgkmcnt(0)
	v_mfma_f32_16x16x32_bf16 v[56:59], v[86:89], v[68:71], v[60:63]
	v_exp_f32_e32 v104, v76
	v_mul_f32_e32 v76, 0x3fb8aa3b, v105
	v_exp_f32_e32 v105, v76
	ds_read2_b64 v[60:63], v160 offset0:160 offset1:164
	s_waitcnt lgkmcnt(0)
	v_mfma_f32_16x16x32_bf16 v[52:55], v[60:63], v[72:75], v[52:55]
	v_cvt_pk_bf16_f32 v76, v102, v103
	v_cvt_pk_bf16_f32 v77, v104, v105
	v_cvt_pk_bf16_f32 v78, v116, v117
	v_mfma_f32_16x16x32_bf16 v[44:47], v[60:63], v[80:83], v[44:47]
	ds_read2_b64 v[60:63], v160 offset0:168 offset1:172
	v_cvt_pk_bf16_f32 v79, v118, v119
	s_waitcnt lgkmcnt(0)
	v_mfma_f32_16x16x32_bf16 v[52:55], v[60:63], v[68:71], v[52:55]
	v_mfma_f32_16x16x32_bf16 v[60:63], v[60:63], v[76:79], v[44:47]
	s_nop 2
	ds_read2_b64 v[44:47], v162 offset0:192 offset1:196
	v_mfma_f32_16x16x32_bf16 v[64:67], v[86:89], v[76:79], v[64:67]
	ds_read2_b64 v[86:89], v162 offset0:200 offset1:204
	s_waitcnt lgkmcnt(1)
	v_mfma_f32_16x16x32_bf16 v[48:51], v[44:47], v[72:75], v[48:51]
	v_mfma_f32_16x16x32_bf16 v[36:39], v[44:47], v[80:83], v[36:39]
	s_waitcnt lgkmcnt(0)
	v_mfma_f32_16x16x32_bf16 v[44:47], v[86:89], v[68:71], v[48:51]
	v_mfma_f32_16x16x32_bf16 v[48:51], v[86:89], v[76:79], v[36:39]
	ds_read2_b64 v[86:89], v163 offset0:232 offset1:236
	s_nop 3
	ds_read2_b64 v[36:39], v163 offset0:224 offset1:228
	s_waitcnt lgkmcnt(0)
	v_mfma_f32_16x16x32_bf16 v[40:43], v[36:39], v[72:75], v[40:43]
	v_mfma_f32_16x16x32_bf16 v[28:31], v[36:39], v[80:83], v[28:31]
	v_mfma_f32_16x16x32_bf16 v[36:39], v[86:89], v[68:71], v[40:43]
	v_mfma_f32_16x16x32_bf16 v[40:43], v[86:89], v[76:79], v[28:31]
	ds_read2_b64 v[86:89], v164 offset0:8 offset1:12
	s_nop 4
	ds_read2_b64 v[28:31], v164 offset1:4
	s_waitcnt lgkmcnt(0)
	v_mfma_f32_16x16x32_bf16 v[32:35], v[28:31], v[72:75], v[32:35]
	v_mfma_f32_16x16x32_bf16 v[20:23], v[28:31], v[80:83], v[20:23]
	v_mfma_f32_16x16x32_bf16 v[28:31], v[86:89], v[68:71], v[32:35]
	v_mfma_f32_16x16x32_bf16 v[32:35], v[86:89], v[76:79], v[20:23]
	ds_read2_b64 v[86:89], v165 offset0:40 offset1:44
	s_nop 4
	ds_read2_b64 v[20:23], v165 offset0:32 offset1:36
	s_waitcnt lgkmcnt(0)
	v_mfma_f32_16x16x32_bf16 v[24:27], v[20:23], v[72:75], v[24:27]
	v_mfma_f32_16x16x32_bf16 v[20:23], v[20:23], v[80:83], v[12:15]
	v_mfma_f32_16x16x32_bf16 v[12:15], v[86:89], v[68:71], v[24:27]
	s_nop 5
	ds_read2_b64 v[24:27], v166 offset0:64 offset1:68
	v_mfma_f32_16x16x32_bf16 v[20:23], v[86:89], v[76:79], v[20:23]
	ds_read2_b64 v[86:89], v166 offset0:72 offset1:76
	s_waitcnt lgkmcnt(1)
	v_mfma_f32_16x16x32_bf16 v[16:19], v[24:27], v[72:75], v[16:19]
	v_mfma_f32_16x16x32_bf16 v[24:27], v[24:27], v[80:83], v[4:7]
	s_waitcnt lgkmcnt(0)
	v_mfma_f32_16x16x32_bf16 v[4:7], v[86:89], v[68:71], v[16:19]
	v_mfma_f32_16x16x32_bf16 v[16:19], v[86:89], v[76:79], v[24:27]
	s_nop 4
	ds_read2_b64 v[24:27], v167 offset0:96 offset1:100
	s_waitcnt lgkmcnt(0)
	v_mfma_f32_16x16x32_bf16 v[8:11], v[24:27], v[72:75], v[8:11]
	v_mfma_f32_16x16x32_bf16 v[0:3], v[24:27], v[80:83], v[0:3]
	ds_read2_b64 v[24:27], v167 offset0:104 offset1:108
	s_waitcnt lgkmcnt(0)
	s_barrier
	v_mfma_f32_16x16x32_bf16 v[72:75], v[24:27], v[68:71], v[8:11]
	s_nop 2
	v_and_b32_e32 v9, 64, v205
	v_add_u32_e32 v9, 64, v9
	v_mfma_f32_16x16x32_bf16 v[24:27], v[24:27], v[76:79], v[0:3]
	global_load_dword v8, v131, s[10:11] offset:16
	s_nop 1
	global_load_dword v0, v131, s[10:11]
	v_add_f32_e32 v2, 0, v84
	v_add_f32_e32 v2, v85, v2
	v_add_f32_e32 v2, v106, v2
	v_add_f32_e32 v2, v107, v2
	v_add_f32_e32 v2, v2, v90
	v_add_f32_e32 v2, v91, v2
	v_add_f32_e32 v2, v92, v2
	v_add_f32_e32 v2, v93, v2
	v_add_f32_e32 v2, v2, v98
	v_add_f32_e32 v2, v99, v2
	v_add_f32_e32 v2, v100, v2
	v_add_f32_e32 v2, v101, v2
	v_add_f32_e32 v2, v2, v108
	v_add_f32_e32 v2, v109, v2
	v_xor_b32_e32 v3, 16, v205
	v_add_f32_e32 v1, 0, v112
	v_add_f32_e32 v2, v110, v2
	v_cmp_lt_i32_e32 vcc, v3, v9
	v_add_f32_e32 v1, v113, v1
	v_add_f32_e32 v2, v111, v2
	v_cndmask_b32_e32 v3, v205, v3, vcc
	v_add_f32_e32 v1, v114, v1
	v_add_f32_e32 v2, v152, v2
	v_lshlrev_b32_e32 v69, 2, v3
	v_add_f32_e32 v1, v115, v1
	ds_bpermute_b32 v3, v69, v2
	v_add_f32_e32 v1, v1, v94
	v_add_f32_e32 v1, v95, v1
	v_add_f32_e32 v1, v96, v1
	v_add_f32_e32 v1, v97, v1
	v_add_f32_e32 v1, v1, v102
	s_waitcnt lgkmcnt(0)
	v_add_f32_e32 v2, v2, v3
	v_xor_b32_e32 v3, 32, v205
	v_add_f32_e32 v1, v103, v1
	v_cmp_lt_i32_e32 vcc, v3, v9
	v_add_f32_e32 v1, v104, v1
	v_add_f32_e32 v1, v105, v1
	v_cndmask_b32_e32 v3, v205, v3, vcc
	v_lshlrev_b32_e32 v71, 2, v3
	v_add_f32_e32 v1, v1, v116
	ds_bpermute_b32 v3, v71, v2
	v_add_f32_e32 v1, v117, v1
	v_add_f32_e32 v1, v118, v1
	v_add_f32_e32 v1, v119, v1
	v_add_f32_e32 v1, v153, v1
	s_waitcnt lgkmcnt(0)
	v_add_f32_e32 v2, v2, v3
	ds_bpermute_b32 v3, v69, v1
	s_waitcnt lgkmcnt(0)
	v_add_f32_e32 v1, v1, v3
	ds_bpermute_b32 v3, v71, v1
	s_waitcnt lgkmcnt(0)
	v_add_f32_e32 v1, v1, v3
	v_div_scale_f32 v3, s[0:1], v2, v2, 1.0
	v_rcp_f32_e32 v9, v3
	s_nop 0
	v_fma_f32 v10, -v3, v9, 1.0
	v_fmac_f32_e32 v9, v10, v9
	v_div_scale_f32 v10, vcc, 1.0, v2, 1.0
	v_mul_f32_e32 v11, v10, v9
	v_fma_f32 v68, -v3, v11, v10
	v_fmac_f32_e32 v11, v68, v9
	v_fma_f32 v3, -v3, v11, v10
	v_div_fmas_f32 v3, v3, v9, v11
	v_div_fixup_f32 v68, v3, v2, 1.0
	s_waitcnt vmcnt(0)
	v_div_scale_f32 v2, s[0:1], v1, v1, v0
	v_rcp_f32_e32 v3, v2
	s_movk_i32 s0, 0x4a00
	v_fma_f32 v9, -v2, v3, 1.0
	v_fmac_f32_e32 v3, v9, v3
	v_div_scale_f32 v9, vcc, v0, v1, v0
	v_mul_f32_e32 v10, v9, v3
	v_fma_f32 v11, -v2, v10, v9
	v_fmac_f32_e32 v10, v11, v3
	v_fma_f32 v2, -v2, v10, v9
	v_div_fmas_f32 v2, v2, v3, v10
	v_div_fixup_f32 v70, v2, v1, v0
	v_pk_mul_f32 v[0:1], v[18:19], v[70:71] op_sel_hi:[1,0]
	v_pk_mul_f32 v[64:65], v[64:65], v[70:71] op_sel_hi:[1,0]
	v_pk_fma_f32 v[10:11], v[6:7], v[68:69], v[0:1] op_sel_hi:[1,0,1] neg_lo:[0,0,1] neg_hi:[0,0,1]
	v_mov_b64_e32 v[6:7], s[96:97]
	v_mad_i64_i32 v[6:7], s[0:1], v150, s0, v[6:7]
	v_readlane_b32 s0, v254, 47
	v_pk_mul_f32 v[0:1], v[24:25], v[70:71] op_sel_hi:[1,0]
	v_lshl_add_u64 v[6:7], v[6:7], 0, s[92:93]
	v_readlane_b32 s1, v254, 48
	v_pk_fma_f32 v[2:3], v[72:73], v[68:69], v[0:1] op_sel_hi:[1,0,1] neg_lo:[0,0,1] neg_hi:[0,0,1]
	v_sub_f32_e32 v72, 1.0, v8
	v_lshl_add_u64 v[8:9], v[148:149], 1, s[0:1]
	v_lshl_add_u64 v[6:7], v[6:7], 0, v[146:147]
	s_mov_b64 s[0:1], 0x92a8f00
	v_lshl_add_u64 v[78:79], v[8:9], 0, s[92:93]
	v_lshl_add_u64 v[8:9], v[6:7], 0, s[0:1]
	s_mov_b32 s0, 0x92a8000
	v_add_co_u32_e32 v6, vcc, s0, v6
	v_pk_mul_f32 v[0:1], v[26:27], v[70:71] op_sel_hi:[1,0]
	s_nop 0
	v_addc_co_u32_e32 v7, vcc, 0, v7, vcc
	global_load_dwordx2 v[6:7], v[6:7], off offset:3840
	v_pk_fma_f32 v[0:1], v[74:75], v[68:69], v[0:1] op_sel_hi:[1,0,1] neg_lo:[0,0,1] neg_hi:[0,0,1]
	global_load_dwordx4 v[74:77], v130, s[12:13]
	v_pk_mul_f32 v[66:67], v[66:67], v[70:71] op_sel_hi:[1,0]
	v_pk_fma_f32 v[56:57], v[56:57], v[68:69], v[64:65] op_sel_hi:[1,0,1] neg_lo:[0,0,1] neg_hi:[0,0,1]
	v_pk_fma_f32 v[58:59], v[58:59], v[68:69], v[66:67] op_sel_hi:[1,0,1] neg_lo:[0,0,1] neg_hi:[0,0,1]
	v_pk_mul_f32 v[64:65], v[56:57], v[56:57]
	v_pk_mul_f32 v[66:67], v[58:59], v[58:59]
	v_pk_mul_f32 v[60:61], v[60:61], v[70:71] op_sel_hi:[1,0]
	v_add_f32_e32 v64, v64, v65
	v_pk_fma_f32 v[52:53], v[52:53], v[68:69], v[60:61] op_sel_hi:[1,0,1] neg_lo:[0,0,1] neg_hi:[0,0,1]
	v_add_f32_e32 v64, v66, v64
	v_pk_mul_f32 v[62:63], v[62:63], v[70:71] op_sel_hi:[1,0]
	v_pk_mul_f32 v[60:61], v[52:53], v[52:53]
	v_add_f32_e32 v64, v67, v64
	v_pk_fma_f32 v[54:55], v[54:55], v[68:69], v[62:63] op_sel_hi:[1,0,1] neg_lo:[0,0,1] neg_hi:[0,0,1]
	v_add_f32_e32 v60, v60, v64
	v_pk_mul_f32 v[62:63], v[54:55], v[54:55]
	v_pk_mul_f32 v[48:49], v[48:49], v[70:71] op_sel_hi:[1,0]
	v_add_f32_e32 v60, v61, v60
	v_pk_fma_f32 v[44:45], v[44:45], v[68:69], v[48:49] op_sel_hi:[1,0,1] neg_lo:[0,0,1] neg_hi:[0,0,1]
	v_add_f32_e32 v60, v62, v60
	v_pk_mul_f32 v[50:51], v[50:51], v[70:71] op_sel_hi:[1,0]
	v_pk_mul_f32 v[48:49], v[44:45], v[44:45]
	v_add_f32_e32 v60, v63, v60
	v_pk_fma_f32 v[46:47], v[46:47], v[68:69], v[50:51] op_sel_hi:[1,0,1] neg_lo:[0,0,1] neg_hi:[0,0,1]
	v_add_f32_e32 v48, v48, v60
	v_pk_mul_f32 v[50:51], v[46:47], v[46:47]
	v_pk_mul_f32 v[40:41], v[40:41], v[70:71] op_sel_hi:[1,0]
	v_add_f32_e32 v48, v49, v48
	v_pk_fma_f32 v[36:37], v[36:37], v[68:69], v[40:41] op_sel_hi:[1,0,1] neg_lo:[0,0,1] neg_hi:[0,0,1]
	v_add_f32_e32 v48, v50, v48
	v_pk_mul_f32 v[42:43], v[42:43], v[70:71] op_sel_hi:[1,0]
	v_pk_mul_f32 v[40:41], v[36:37], v[36:37]
	v_add_f32_e32 v48, v51, v48
	v_pk_fma_f32 v[38:39], v[38:39], v[68:69], v[42:43] op_sel_hi:[1,0,1] neg_lo:[0,0,1] neg_hi:[0,0,1]
	v_add_f32_e32 v40, v40, v48
	v_pk_mul_f32 v[42:43], v[38:39], v[38:39]
	v_pk_mul_f32 v[32:33], v[32:33], v[70:71] op_sel_hi:[1,0]
	v_add_f32_e32 v40, v41, v40
	v_pk_fma_f32 v[28:29], v[28:29], v[68:69], v[32:33] op_sel_hi:[1,0,1] neg_lo:[0,0,1] neg_hi:[0,0,1]
	v_add_f32_e32 v40, v42, v40
	v_pk_mul_f32 v[34:35], v[34:35], v[70:71] op_sel_hi:[1,0]
	v_pk_mul_f32 v[32:33], v[28:29], v[28:29]
	v_add_f32_e32 v40, v43, v40
	v_pk_fma_f32 v[30:31], v[30:31], v[68:69], v[34:35] op_sel_hi:[1,0,1] neg_lo:[0,0,1] neg_hi:[0,0,1]
	v_add_f32_e32 v32, v32, v40
	v_pk_mul_f32 v[34:35], v[30:31], v[30:31]
	v_pk_mul_f32 v[20:21], v[20:21], v[70:71] op_sel_hi:[1,0]
	v_add_f32_e32 v32, v33, v32
	v_pk_fma_f32 v[20:21], v[12:13], v[68:69], v[20:21] op_sel_hi:[1,0,1] neg_lo:[0,0,1] neg_hi:[0,0,1]
	v_add_f32_e32 v32, v34, v32
	v_pk_mul_f32 v[22:23], v[22:23], v[70:71] op_sel_hi:[1,0]
	v_pk_mul_f32 v[12:13], v[20:21], v[20:21]
	v_add_f32_e32 v32, v35, v32
	v_pk_fma_f32 v[22:23], v[14:15], v[68:69], v[22:23] op_sel_hi:[1,0,1] neg_lo:[0,0,1] neg_hi:[0,0,1]
	v_add_f32_e32 v12, v12, v32
	v_pk_mul_f32 v[14:15], v[22:23], v[22:23]
	v_pk_mul_f32 v[16:17], v[16:17], v[70:71] op_sel_hi:[1,0]
	v_add_f32_e32 v12, v13, v12
	v_pk_fma_f32 v[16:17], v[4:5], v[68:69], v[16:17] op_sel_hi:[1,0,1] neg_lo:[0,0,1] neg_hi:[0,0,1]
	v_add_f32_e32 v12, v14, v12
	v_pk_mul_f32 v[4:5], v[16:17], v[16:17]
	v_add_f32_e32 v12, v15, v12
	v_add_f32_e32 v4, v4, v12
	v_pk_mul_f32 v[18:19], v[10:11], v[10:11]
	v_add_f32_e32 v4, v5, v4
	v_add_f32_e32 v4, v18, v4
	v_pk_mul_f32 v[24:25], v[2:3], v[2:3]
	v_add_f32_e32 v4, v19, v4
	v_add_f32_e32 v4, v24, v4
	v_pk_mul_f32 v[26:27], v[0:1], v[0:1]
	v_add_f32_e32 v4, v25, v4
	v_add_f32_e32 v4, v26, v4
	v_add_f32_e32 v4, v27, v4
	ds_bpermute_b32 v5, v69, v4
	s_waitcnt vmcnt(1)
	v_lshlrev_b32_e32 v80, 16, v6
	v_mul_f32_e32 v73, 0xbfb8aa3b, v80
	v_exp_f32_e32 v73, v73
	v_and_b32_e32 v81, 0xffff0000, v6
	v_lshlrev_b32_e32 v6, 16, v7
	v_and_b32_e32 v7, 0xffff0000, v7
	v_add_f32_e32 v73, 1.0, v73
	v_rcp_f32_e32 v82, v73
	v_mul_f32_e32 v73, 0xbfb8aa3b, v81
	v_exp_f32_e32 v73, v73
	s_waitcnt lgkmcnt(0)
	v_add_f32_e32 v4, v4, v5
	ds_bpermute_b32 v5, v71, v4
	v_add_f32_e32 v73, 1.0, v73
	v_rcp_f32_e32 v83, v73
	v_mul_f32_e32 v73, 0xbfb8aa3b, v6
	v_exp_f32_e32 v73, v73
	s_waitcnt lgkmcnt(0)
	v_add_f32_e32 v4, v4, v5
	v_pk_mul_f32 v[80:81], v[82:83], v[80:81]
	v_fmamk_f32 v4, v4, 0x3c000000, v210
	v_add_f32_e32 v73, 1.0, v73
	v_rcp_f32_e32 v82, v73
	v_mul_f32_e32 v73, 0xbfb8aa3b, v7
	v_exp_f32_e32 v73, v73
	v_rsq_f32_e32 v4, v4
	v_add_f32_e32 v73, 1.0, v73
	v_rcp_f32_e32 v83, v73
	v_mul_f32_e32 v4, v72, v4
	v_pk_mul_f32 v[12:13], v[56:57], v[4:5] op_sel_hi:[1,0]
	v_pk_mul_f32 v[14:15], v[58:59], v[4:5] op_sel_hi:[1,0]
	v_pk_mul_f32 v[82:83], v[82:83], v[6:7]
	v_lshl_add_u64 v[6:7], v[78:79], 0, v[146:147]
	global_load_dwordx2 v[78:79], v[8:9], off offset:32
	s_waitcnt vmcnt(1)
	v_pk_mul_f32 v[12:13], v[74:75], v[12:13]
	v_pk_mul_f32 v[14:15], v[76:77], v[14:15]
	v_pk_mul_f32 v[12:13], v[80:81], v[12:13]
	v_pk_mul_f32 v[14:15], v[82:83], v[14:15]
	v_cvt_pk_bf16_f32 v12, v12, v13
	v_cvt_pk_bf16_f32 v13, v14, v15
	global_store_dwordx2 v[6:7], v[12:13], off
	global_load_dwordx4 v[12:15], v130, s[12:13] offset:64
	v_pk_mul_f32 v[18:19], v[52:53], v[4:5] op_sel_hi:[1,0]
	s_waitcnt vmcnt(2)
	v_lshlrev_b32_e32 v84, 16, v78
	v_mul_f32_e32 v73, 0xbfb8aa3b, v84
	v_exp_f32_e32 v73, v73
	v_and_b32_e32 v85, 0xffff0000, v78
	v_lshlrev_b32_e32 v78, 16, v79
	v_and_b32_e32 v79, 0xffff0000, v79
	v_add_f32_e32 v73, 1.0, v73
	v_rcp_f32_e32 v86, v73
	v_mul_f32_e32 v73, 0xbfb8aa3b, v85
	v_exp_f32_e32 v73, v73
	s_waitcnt vmcnt(0)
	v_pk_mul_f32 v[12:13], v[12:13], v[18:19]
	v_pk_mul_f32 v[18:19], v[54:55], v[4:5] op_sel_hi:[1,0]
	v_add_f32_e32 v73, 1.0, v73
	v_rcp_f32_e32 v87, v73
	v_mul_f32_e32 v73, 0xbfb8aa3b, v78
	v_exp_f32_e32 v73, v73
	v_pk_mul_f32 v[14:15], v[14:15], v[18:19]
	v_pk_mul_f32 v[84:85], v[86:87], v[84:85]
	v_pk_mul_f32 v[18:19], v[44:45], v[4:5] op_sel_hi:[1,0]
	v_add_f32_e32 v73, 1.0, v73
	v_rcp_f32_e32 v86, v73
	v_mul_f32_e32 v73, 0xbfb8aa3b, v79
	v_exp_f32_e32 v73, v73
	v_pk_mul_f32 v[12:13], v[84:85], v[12:13]
	v_add_f32_e32 v73, 1.0, v73
	v_rcp_f32_e32 v87, v73
	v_cvt_pk_bf16_f32 v12, v12, v13
	v_pk_mul_f32 v[78:79], v[86:87], v[78:79]
	global_load_dwordx2 v[86:87], v[8:9], off offset:64
	v_pk_mul_f32 v[14:15], v[78:79], v[14:15]
	s_waitcnt vmcnt(0)
	v_lshlrev_b32_e32 v88, 16, v86
	v_mul_f32_e32 v73, 0xbfb8aa3b, v88
	v_exp_f32_e32 v73, v73
	v_and_b32_e32 v89, 0xffff0000, v86
	v_lshlrev_b32_e32 v86, 16, v87
	v_and_b32_e32 v87, 0xffff0000, v87
	v_add_f32_e32 v73, 1.0, v73
	v_rcp_f32_e32 v90, v73
	v_mul_f32_e32 v73, 0xbfb8aa3b, v89
	v_exp_f32_e32 v73, v73
	v_cvt_pk_bf16_f32 v13, v14, v15
	global_store_dwordx2 v[6:7], v[12:13], off offset:32
	global_load_dwordx4 v[12:15], v130, s[12:13] offset:128
	v_add_f32_e32 v73, 1.0, v73
	v_rcp_f32_e32 v91, v73
	v_mul_f32_e32 v73, 0xbfb8aa3b, v86
	v_exp_f32_e32 v73, v73
	v_pk_mul_f32 v[88:89], v[90:91], v[88:89]
	v_add_f32_e32 v73, 1.0, v73
	v_rcp_f32_e32 v90, v73
	v_mul_f32_e32 v73, 0xbfb8aa3b, v87
	v_exp_f32_e32 v73, v73
	s_waitcnt vmcnt(0)
	v_pk_mul_f32 v[12:13], v[12:13], v[18:19]
	v_add_f32_e32 v73, 1.0, v73
	v_rcp_f32_e32 v91, v73
	v_pk_mul_f32 v[18:19], v[46:47], v[4:5] op_sel_hi:[1,0]
	v_pk_mul_f32 v[12:13], v[88:89], v[12:13]
	v_pk_mul_f32 v[14:15], v[14:15], v[18:19]
	v_pk_mul_f32 v[86:87], v[90:91], v[86:87]
	global_load_dwordx2 v[90:91], v[8:9], off offset:96
	v_pk_mul_f32 v[14:15], v[86:87], v[14:15]
	v_cvt_pk_bf16_f32 v12, v12, v13
	v_cvt_pk_bf16_f32 v13, v14, v15
	global_store_dwordx2 v[6:7], v[12:13], off offset:64
	global_load_dwordx4 v[12:15], v130, s[12:13] offset:192
	v_pk_mul_f32 v[18:19], v[36:37], v[4:5] op_sel_hi:[1,0]
	s_waitcnt vmcnt(2)
	v_lshlrev_b32_e32 v92, 16, v90
	v_mul_f32_e32 v73, 0xbfb8aa3b, v92
	v_exp_f32_e32 v73, v73
	v_and_b32_e32 v93, 0xffff0000, v90
	v_lshlrev_b32_e32 v90, 16, v91
	v_and_b32_e32 v91, 0xffff0000, v91
	v_add_f32_e32 v73, 1.0, v73
	v_rcp_f32_e32 v94, v73
	v_mul_f32_e32 v73, 0xbfb8aa3b, v93
	v_exp_f32_e32 v73, v73
	s_waitcnt vmcnt(0)
	v_pk_mul_f32 v[12:13], v[12:13], v[18:19]
	v_pk_mul_f32 v[18:19], v[38:39], v[4:5] op_sel_hi:[1,0]
	v_add_f32_e32 v73, 1.0, v73
	v_rcp_f32_e32 v95, v73
	v_mul_f32_e32 v73, 0xbfb8aa3b, v90
	v_exp_f32_e32 v73, v73
	v_pk_mul_f32 v[14:15], v[14:15], v[18:19]
	v_pk_mul_f32 v[92:93], v[94:95], v[92:93]
	v_pk_mul_f32 v[18:19], v[28:29], v[4:5] op_sel_hi:[1,0]
	v_add_f32_e32 v73, 1.0, v73
	v_rcp_f32_e32 v94, v73
	v_mul_f32_e32 v73, 0xbfb8aa3b, v91
	v_exp_f32_e32 v73, v73
	v_pk_mul_f32 v[12:13], v[92:93], v[12:13]
	v_add_f32_e32 v73, 1.0, v73
	v_rcp_f32_e32 v95, v73
	v_cvt_pk_bf16_f32 v12, v12, v13
	v_pk_mul_f32 v[90:91], v[94:95], v[90:91]
	global_load_dwordx2 v[94:95], v[8:9], off offset:128
	v_pk_mul_f32 v[14:15], v[90:91], v[14:15]
	s_waitcnt vmcnt(0)
	v_lshlrev_b32_e32 v96, 16, v94
	v_cvt_pk_bf16_f32 v13, v14, v15
	global_store_dwordx2 v[6:7], v[12:13], off offset:96
	global_load_dwordx4 v[12:15], v130, s[12:13] offset:256
	v_mul_f32_e32 v73, 0xbfb8aa3b, v96
	v_exp_f32_e32 v73, v73
	v_and_b32_e32 v97, 0xffff0000, v94
	v_lshlrev_b32_e32 v94, 16, v95
	v_and_b32_e32 v95, 0xffff0000, v95
	v_add_f32_e32 v73, 1.0, v73
	v_rcp_f32_e32 v98, v73
	v_mul_f32_e32 v73, 0xbfb8aa3b, v97
	v_exp_f32_e32 v73, v73
	s_waitcnt vmcnt(0)
	v_pk_mul_f32 v[12:13], v[12:13], v[18:19]
	v_add_f32_e32 v73, 1.0, v73
	v_rcp_f32_e32 v99, v73
	v_mul_f32_e32 v73, 0xbfb8aa3b, v94
	v_exp_f32_e32 v73, v73
	v_pk_mul_f32 v[18:19], v[30:31], v[4:5] op_sel_hi:[1,0]
	v_pk_mul_f32 v[96:97], v[98:99], v[96:97]
	v_pk_mul_f32 v[14:15], v[14:15], v[18:19]
	v_add_f32_e32 v73, 1.0, v73
	v_rcp_f32_e32 v98, v73
	v_mul_f32_e32 v73, 0xbfb8aa3b, v95
	v_exp_f32_e32 v73, v73
	v_pk_mul_f32 v[12:13], v[96:97], v[12:13]
	v_pk_mul_f32 v[18:19], v[20:21], v[4:5] op_sel_hi:[1,0]
	v_cvt_pk_bf16_f32 v12, v12, v13
	v_add_f32_e32 v73, 1.0, v73
	v_rcp_f32_e32 v99, v73
	s_nop 0
	v_pk_mul_f32 v[94:95], v[98:99], v[94:95]
	global_load_dwordx2 v[98:99], v[8:9], off offset:160
	v_pk_mul_f32 v[14:15], v[94:95], v[14:15]
	s_waitcnt vmcnt(0)
	v_lshlrev_b32_e32 v100, 16, v98
	v_cvt_pk_bf16_f32 v13, v14, v15
	global_store_dwordx2 v[6:7], v[12:13], off offset:128
	global_load_dwordx4 v[12:15], v130, s[12:13] offset:320
	v_mul_f32_e32 v73, 0xbfb8aa3b, v100
	v_exp_f32_e32 v73, v73
	v_and_b32_e32 v101, 0xffff0000, v98
	v_lshlrev_b32_e32 v98, 16, v99
	v_and_b32_e32 v99, 0xffff0000, v99
	v_add_f32_e32 v73, 1.0, v73
	v_rcp_f32_e32 v102, v73
	v_mul_f32_e32 v73, 0xbfb8aa3b, v101
	v_exp_f32_e32 v73, v73
	s_waitcnt vmcnt(0)
	v_pk_mul_f32 v[12:13], v[18:19], v[12:13]
	v_add_f32_e32 v73, 1.0, v73
	v_rcp_f32_e32 v103, v73
	v_mul_f32_e32 v73, 0xbfb8aa3b, v98
	v_exp_f32_e32 v73, v73
	v_pk_mul_f32 v[18:19], v[22:23], v[4:5] op_sel_hi:[1,0]
	v_pk_mul_f32 v[100:101], v[102:103], v[100:101]
	v_pk_mul_f32 v[14:15], v[18:19], v[14:15]
	v_add_f32_e32 v73, 1.0, v73
	v_rcp_f32_e32 v102, v73
	v_mul_f32_e32 v73, 0xbfb8aa3b, v99
	v_exp_f32_e32 v73, v73
	v_pk_mul_f32 v[12:13], v[12:13], v[100:101]
	v_add_f32_e32 v73, 1.0, v73
	v_rcp_f32_e32 v103, v73
	v_cvt_pk_bf16_f32 v12, v12, v13
	v_pk_mul_f32 v[98:99], v[102:103], v[98:99]
	s_nop 0
	v_pk_mul_f32 v[14:15], v[14:15], v[98:99]
	s_nop 0
	v_cvt_pk_bf16_f32 v13, v14, v15
	global_store_dwordx2 v[6:7], v[12:13], off offset:160
	global_load_dwordx2 v[18:19], v[8:9], off offset:192
	s_nop 0
	global_load_dwordx4 v[12:15], v130, s[12:13] offset:384
	s_waitcnt vmcnt(1)
	v_lshlrev_b32_e32 v20, 16, v18
	v_mul_f32_e32 v5, 0xbfb8aa3b, v20
	v_exp_f32_e32 v5, v5
	v_and_b32_e32 v21, 0xffff0000, v18
	global_load_dwordx2 v[8:9], v[8:9], off offset:224
	v_add_f32_e32 v5, 1.0, v5
	v_rcp_f32_e32 v22, v5
	v_pk_mul_f32 v[16:17], v[16:17], v[4:5] op_sel_hi:[1,0]
	v_mul_f32_e32 v5, 0xbfb8aa3b, v21
	v_exp_f32_e32 v5, v5
	s_waitcnt vmcnt(1)
	v_pk_mul_f32 v[12:13], v[16:17], v[12:13]
	v_add_f32_e32 v5, 1.0, v5
	v_rcp_f32_e32 v23, v5
	s_nop 0
	v_pk_mul_f32 v[16:17], v[22:23], v[20:21]
	s_nop 0
	v_pk_mul_f32 v[12:13], v[12:13], v[16:17]
	v_lshlrev_b32_e32 v16, 16, v19
	v_mul_f32_e32 v5, 0xbfb8aa3b, v16
	v_exp_f32_e32 v5, v5
	v_and_b32_e32 v17, 0xffff0000, v19
	v_cvt_pk_bf16_f32 v12, v12, v13
	v_add_f32_e32 v5, 1.0, v5
	v_rcp_f32_e32 v18, v5
	v_pk_mul_f32 v[10:11], v[10:11], v[4:5] op_sel_hi:[1,0]
	v_mul_f32_e32 v5, 0xbfb8aa3b, v17
	v_exp_f32_e32 v5, v5
	v_pk_mul_f32 v[10:11], v[10:11], v[14:15]
	v_add_f32_e32 v5, 1.0, v5
	v_rcp_f32_e32 v19, v5
	s_nop 0
	v_pk_mul_f32 v[14:15], v[18:19], v[16:17]
	s_nop 0
	v_pk_mul_f32 v[10:11], v[10:11], v[14:15]
	s_nop 0
	v_cvt_pk_bf16_f32 v13, v10, v11
	global_store_dwordx2 v[6:7], v[12:13], off offset:192
	global_load_dwordx4 v[12:15], v130, s[12:13] offset:448
	s_waitcnt vmcnt(2)
	v_lshlrev_b32_e32 v10, 16, v8
	v_mul_f32_e32 v5, 0xbfb8aa3b, v10
	v_exp_f32_e32 v5, v5
	v_and_b32_e32 v11, 0xffff0000, v8
	v_lshlrev_b32_e32 v8, 16, v9
	v_and_b32_e32 v9, 0xffff0000, v9
	v_add_f32_e32 v5, 1.0, v5
	v_rcp_f32_e32 v16, v5
	v_pk_mul_f32 v[2:3], v[2:3], v[4:5] op_sel_hi:[1,0]
	v_mul_f32_e32 v5, 0xbfb8aa3b, v11
	v_exp_f32_e32 v5, v5
	s_waitcnt vmcnt(0)
	v_pk_mul_f32 v[2:3], v[2:3], v[12:13]
	v_add_f32_e32 v5, 1.0, v5
	v_rcp_f32_e32 v17, v5
	v_mul_f32_e32 v5, 0xbfb8aa3b, v8
	v_exp_f32_e32 v5, v5
	v_pk_mul_f32 v[10:11], v[16:17], v[10:11]
	s_nop 0
	v_pk_mul_f32 v[2:3], v[2:3], v[10:11]
	v_add_f32_e32 v5, 1.0, v5
	v_pk_mul_f32 v[0:1], v[0:1], v[4:5] op_sel_hi:[1,0]
	v_mul_f32_e32 v4, 0xbfb8aa3b, v9
	v_exp_f32_e32 v4, v4
	v_rcp_f32_e32 v10, v5
	v_pk_mul_f32 v[0:1], v[0:1], v[14:15]
	v_cvt_pk_bf16_f32 v2, v2, v3
	v_add_f32_e32 v4, 1.0, v4
	v_rcp_f32_e32 v11, v4
	s_nop 0
	v_pk_mul_f32 v[4:5], v[10:11], v[8:9]
	s_nop 0
	v_pk_mul_f32 v[0:1], v[0:1], v[4:5]
	s_nop 0
	v_cvt_pk_bf16_f32 v3, v0, v1
	global_store_dwordx2 v[6:7], v[2:3], off offset:224

.LBB0_127:
	s_waitcnt vmcnt(0)
	ds_write_b128 v158, v[100:103]
	ds_write_b128 v158, v[104:107] offset:4352
	ds_write_b128 v158, v[96:99] offset:8704
	ds_write_b128 v158, v[88:91] offset:13056
	ds_write_b128 v151, v[108:111] offset:17408
	ds_write_b128 v151, v[92:95] offset:22016
	ds_write_b128 v151, v[84:87] offset:26624
	ds_write_b128 v151, v[80:83] offset:31232
	s_waitcnt lgkmcnt(0)
	s_barrier
	v_lshl_add_u64 v[80:81], s[96:97], 0, v[156:157]
	s_mov_b32 s26, 0x202b6000
	v_add_co_u32_e32 v84, vcc, s26, v80
	s_nop 1
	v_addc_co_u32_e32 v85, vcc, 0, v81, vcc
	s_mov_b32 s26, 0x202ba000
	global_load_dwordx4 v[100:103], v[84:85], off offset:256
	v_add_co_u32_e32 v84, vcc, s26, v80
	s_nop 1
	v_addc_co_u32_e32 v85, vcc, 0, v81, vcc
	s_mov_b32 s26, 0x202be000
	global_load_dwordx4 v[104:107], v[84:85], off offset:256
	v_add_co_u32_e32 v84, vcc, s26, v80
	s_nop 1
	v_addc_co_u32_e32 v85, vcc, 0, v81, vcc
	s_mov_b32 s26, 0x202c2000
	v_add_co_u32_e32 v80, vcc, s26, v80
	s_nop 1
	v_lshl_add_u64 v[82:83], s[96:97], 0, v[154:155]
	v_addc_co_u32_e32 v81, vcc, 0, v81, vcc
	s_mov_b32 s26, 0x20b26000
	global_load_dwordx4 v[96:99], v[84:85], off offset:256
	global_load_dwordx4 v[88:91], v[80:81], off offset:256
	v_add_co_u32_e32 v80, vcc, s26, v82
	s_nop 1
	v_addc_co_u32_e32 v81, vcc, 0, v83, vcc
	s_mov_b32 s26, 0x20b4a000
	global_load_dwordx4 v[108:111], v[80:81], off offset:384
	v_add_co_u32_e32 v80, vcc, s26, v82
	s_nop 1
	v_addc_co_u32_e32 v81, vcc, 0, v83, vcc
	s_mov_b32 s26, 0x20b6e000
	global_load_dwordx4 v[92:95], v[80:81], off offset:384
	v_add_co_u32_e32 v80, vcc, s26, v82
	s_nop 1
	s_mov_b32 s26, 0x20b92000
	v_addc_co_u32_e32 v81, vcc, 0, v83, vcc
	global_load_dwordx4 v[84:87], v[80:81], off offset:384
	v_add_co_u32_e32 v80, vcc, s26, v82
	s_nop 1
	v_addc_co_u32_e32 v81, vcc, 0, v83, vcc
	global_load_dwordx4 v[80:83], v[80:81], off offset:384
	ds_read_b128 v[112:115], v147
	ds_read_b128 v[116:119], v147 offset:64
	s_nop 0
	s_nop 0
	s_nop 0
	s_waitcnt lgkmcnt(1)
	v_mfma_f32_16x16x32_bf16 v[112:115], v[112:115], v[76:79], 0
	ds_read_b128 v[120:123], v147 offset:192
	s_nop 0
	s_waitcnt lgkmcnt(1)
	v_mfma_f32_16x16x32_bf16 v[112:115], v[116:119], v[72:75], v[112:115]
	ds_read_b128 v[116:119], v147 offset:128
	s_nop 0
	s_nop 0
	s_nop 0
	s_waitcnt lgkmcnt(0)
	v_mfma_f32_16x16x32_bf16 v[116:119], v[116:119], v[68:71], 0
	ds_read_b128 v[124:127], v147 offset:4416
	s_nop 0
	v_mul_f32_e32 v112, 0x3fb8aa3b, v112
	v_exp_f32_e32 v132, v112
	v_mfma_f32_16x16x32_bf16 v[120:123], v[120:123], v[64:67], v[116:119]
	v_mul_f32_e32 v112, 0x3fb8aa3b, v113
	v_exp_f32_e32 v134, v112
	v_mul_f32_e32 v112, 0x3fb8aa3b, v114
	ds_read_b128 v[116:119], v147 offset:4352
	s_waitcnt lgkmcnt(0)
	v_mfma_f32_16x16x32_bf16 v[116:119], v[116:119], v[76:79], 0
	ds_read_b128 v[160:163], v147 offset:4544
	s_nop 0
	v_mul_f32_e32 v120, 0x3fb8aa3b, v120
	v_exp_f32_e32 v133, v120
	v_mfma_f32_16x16x32_bf16 v[116:119], v[124:127], v[72:75], v[116:119]
	ds_read_b128 v[124:127], v147 offset:4480
	v_mul_f32_e32 v120, 0x3fb8aa3b, v121
	v_exp_f32_e32 v135, v120
	s_waitcnt lgkmcnt(0)
	v_mfma_f32_16x16x32_bf16 v[124:127], v[124:127], v[68:71], 0
	ds_read_b128 v[164:167], v147 offset:8768
	v_mul_f32_e32 v120, 0x3fb8aa3b, v122
	v_exp_f32_e32 v136, v112
	v_mfma_f32_16x16x32_bf16 v[124:127], v[160:163], v[64:67], v[124:127]
	ds_read_b128 v[160:163], v147 offset:8704
	v_mul_f32_e32 v112, 0x3fb8aa3b, v115
	ds_read_b128 v[168:171], v147 offset:8896
	s_waitcnt lgkmcnt(1)
	v_mfma_f32_16x16x32_bf16 v[160:163], v[160:163], v[76:79], 0
	v_exp_f32_e32 v137, v120
	v_mul_f32_e32 v120, 0x3fb8aa3b, v123
	v_exp_f32_e32 v138, v112
	v_mfma_f32_16x16x32_bf16 v[160:163], v[164:167], v[72:75], v[160:163]
	ds_read_b128 v[164:167], v147 offset:8832
	ds_read_b128 v[172:175], v147 offset:13120
	v_mul_f32_e32 v112, 0x3fb8aa3b, v116
	s_waitcnt lgkmcnt(1)
	v_mfma_f32_16x16x32_bf16 v[164:167], v[164:167], v[68:71], 0
	v_exp_f32_e32 v139, v120
	v_mul_f32_e32 v120, 0x3fb8aa3b, v124
	v_exp_f32_e32 v140, v112
	v_mfma_f32_16x16x32_bf16 v[164:167], v[168:171], v[64:67], v[164:167]
	ds_read_b128 v[168:171], v147 offset:13056
	ds_read_b128 v[176:179], v147 offset:13248
	v_mul_f32_e32 v112, 0x3fb8aa3b, v117
	s_waitcnt lgkmcnt(1)
	v_mfma_f32_16x16x32_bf16 v[168:171], v[168:171], v[76:79], 0
	v_exp_f32_e32 v141, v120
	v_mul_f32_e32 v120, 0x3fb8aa3b, v125
	v_exp_f32_e32 v142, v112
	v_mfma_f32_16x16x32_bf16 v[168:171], v[172:175], v[72:75], v[168:171]
	ds_read_b128 v[172:175], v147 offset:13184
	v_mul_f32_e32 v112, 0x3fb8aa3b, v118
	v_exp_f32_e32 v143, v120
	s_waitcnt lgkmcnt(0)
	v_mfma_f32_16x16x32_bf16 v[172:175], v[172:175], v[68:71], 0
	v_add_f32_e64 v120, v132, 0
	v_add_f32_e64 v121, v133, 0
	v_mul_f32_e32 v122, 0x3fb8aa3b, v126
	v_pk_add_f32 v[120:121], v[134:135], v[120:121]
	v_mfma_f32_16x16x32_bf16 v[172:175], v[176:179], v[64:67], v[172:175]
	v_exp_f32_e32 v176, v112
	v_mul_f32_e32 v112, 0x3fb8aa3b, v119
	v_exp_f32_e32 v177, v122
	v_mul_f32_e32 v122, 0x3fb8aa3b, v127
	v_exp_f32_e32 v178, v112
	v_mul_f32_e32 v112, 0x3fb8aa3b, v160
	v_pk_add_f32 v[120:121], v[136:137], v[120:121]
	v_exp_f32_e32 v179, v122
	v_mul_f32_e32 v122, 0x3fb8aa3b, v164
	v_exp_f32_e32 v160, v112
	v_mul_f32_e32 v112, 0x3fb8aa3b, v161
	v_pk_add_f32 v[120:121], v[138:139], v[120:121]
	v_exp_f32_e32 v161, v122
	v_mul_f32_e32 v122, 0x3fb8aa3b, v165
	v_exp_f32_e32 v180, v112
	v_mul_f32_e32 v112, 0x3fb8aa3b, v162
	v_pk_add_f32 v[120:121], v[120:121], v[140:141]
	v_exp_f32_e32 v181, v122
	v_mul_f32_e32 v122, 0x3fb8aa3b, v166
	v_exp_f32_e32 v162, v112
	v_mul_f32_e32 v112, 0x3fb8aa3b, v163
	v_pk_add_f32 v[120:121], v[142:143], v[120:121]
	v_exp_f32_e32 v163, v122
	v_mul_f32_e32 v122, 0x3fb8aa3b, v167
	v_exp_f32_e32 v182, v112
	v_exp_f32_e32 v183, v122
	v_pk_add_f32 v[120:121], v[176:177], v[120:121]
	v_mul_f32_e32 v112, 0x3fb8aa3b, v168
	v_pk_add_f32 v[120:121], v[178:179], v[120:121]
	v_mul_f32_e32 v122, 0x3fb8aa3b, v172
	v_pk_add_f32 v[120:121], v[120:121], v[160:161]
	v_cvt_pk_bf16_f32 v124, v161, v181
	v_pk_add_f32 v[120:121], v[180:181], v[120:121]
	v_add_u32_e32 v161, 0x4000, v159
	v_exp_f32_e32 v168, v112
	v_mul_f32_e32 v112, 0x3fb8aa3b, v169
	v_cvt_pk_bf16_f32 v113, v162, v182
	v_exp_f32_e32 v169, v122
	v_mul_f32_e32 v122, 0x3fb8aa3b, v173
	v_pk_add_f32 v[120:121], v[162:163], v[120:121]
	v_cvt_pk_bf16_f32 v125, v163, v183
	ds_read2_b64 v[162:165], v161 offset0:128 offset1:132
	v_exp_f32_e32 v184, v112
	v_mul_f32_e32 v112, 0x3fb8aa3b, v170
	v_exp_f32_e32 v185, v122
	v_mul_f32_e32 v122, 0x3fb8aa3b, v174
	v_exp_f32_e32 v170, v112
	v_mul_f32_e32 v112, 0x3fb8aa3b, v171
	v_exp_f32_e32 v171, v122
	v_mul_f32_e32 v122, 0x3fb8aa3b, v175
	v_exp_f32_e32 v186, v112
	v_exp_f32_e32 v187, v122
	v_pk_add_f32 v[120:121], v[182:183], v[120:121]
	v_cvt_pk_bf16_f32 v116, v132, v134
	v_pk_add_f32 v[120:121], v[120:121], v[168:169]
	v_cvt_pk_bf16_f32 v117, v136, v138
	v_pk_add_f32 v[120:121], v[184:185], v[120:121]
	v_cvt_pk_bf16_f32 v118, v140, v142
	v_pk_add_f32 v[120:121], v[170:171], v[120:121]
	v_cvt_pk_bf16_f32 v119, v176, v178
	v_pk_add_f32 v[120:121], v[186:187], v[120:121]
	v_cvt_pk_bf16_f32 v122, v141, v143
	v_pk_add_f32 v[152:153], v[152:153], v[120:121]
	v_cvt_pk_bf16_f32 v120, v133, v135
	v_cvt_pk_bf16_f32 v121, v137, v139
	v_cvt_pk_bf16_f32 v123, v177, v179
	s_waitcnt lgkmcnt(0)
	v_mfma_f32_16x16x32_bf16 v[60:63], v[162:165], v[116:119], v[60:63]
	v_cvt_pk_bf16_f32 v112, v160, v180
	v_cvt_pk_bf16_f32 v114, v168, v184
	v_cvt_pk_bf16_f32 v115, v170, v186
	v_mfma_f32_16x16x32_bf16 v[56:59], v[162:165], v[120:123], v[56:59]
	ds_read2_b64 v[162:165], v161 offset0:136 offset1:140
	v_cvt_pk_bf16_f32 v126, v169, v185
	v_cvt_pk_bf16_f32 v127, v171, v187
	v_add_u32_e32 v160, 0x4800, v159
	s_waitcnt lgkmcnt(0)
	v_mfma_f32_16x16x32_bf16 v[60:63], v[162:165], v[112:115], v[60:63]
	s_nop 0
	s_nop 0
	v_mfma_f32_16x16x32_bf16 v[56:59], v[162:165], v[124:127], v[56:59]
	ds_read2_b64 v[162:165], v160 offset0:160 offset1:164
	s_nop 0
	s_nop 0
	s_waitcnt lgkmcnt(0)
	v_mfma_f32_16x16x32_bf16 v[52:55], v[162:165], v[116:119], v[52:55]
	s_nop 0
	s_nop 0
	v_mfma_f32_16x16x32_bf16 v[44:47], v[162:165], v[120:123], v[44:47]
	ds_read2_b64 v[162:165], v160 offset0:168 offset1:172
	s_nop 0
	s_waitcnt lgkmcnt(0)
	v_mfma_f32_16x16x32_bf16 v[52:55], v[162:165], v[112:115], v[52:55]
	s_nop 0
	s_nop 0
	v_mfma_f32_16x16x32_bf16 v[44:47], v[162:165], v[124:127], v[44:47]
	v_add_u32_e32 v162, 0x5000, v159
	ds_read2_b64 v[164:167], v162 offset0:192 offset1:196
	v_add_u32_e32 v163, 0x5800, v159
	s_waitcnt lgkmcnt(0)
	v_mfma_f32_16x16x32_bf16 v[48:51], v[164:167], v[116:119], v[48:51]
	s_nop 0
	s_nop 0
	s_nop 0
	v_mfma_f32_16x16x32_bf16 v[36:39], v[164:167], v[120:123], v[36:39]
	ds_read2_b64 v[164:167], v162 offset0:200 offset1:204
	s_nop 0
	s_waitcnt lgkmcnt(0)
	v_mfma_f32_16x16x32_bf16 v[48:51], v[164:167], v[112:115], v[48:51]
	s_nop 0
	s_nop 0
	v_mfma_f32_16x16x32_bf16 v[36:39], v[164:167], v[124:127], v[36:39]
	ds_read2_b64 v[164:167], v163 offset0:224 offset1:228
	s_nop 0
	s_nop 0
	s_waitcnt lgkmcnt(0)
	v_mfma_f32_16x16x32_bf16 v[40:43], v[164:167], v[116:119], v[40:43]
	s_nop 0
	s_nop 0
	v_mfma_f32_16x16x32_bf16 v[28:31], v[164:167], v[120:123], v[28:31]
	ds_read2_b64 v[164:167], v163 offset0:232 offset1:236
	s_nop 0
	s_nop 0
	s_nop 0
	s_nop 0
	s_nop 0
	s_nop 0
	s_nop 0
	s_waitcnt lgkmcnt(0)
	v_mfma_f32_16x16x32_bf16 v[40:43], v[164:167], v[112:115], v[40:43]
	s_nop 0
	s_nop 0
	v_mfma_f32_16x16x32_bf16 v[28:31], v[164:167], v[124:127], v[28:31]
	v_add_u32_e32 v164, 0x6800, v159
	ds_read2_b64 v[166:169], v164 offset1:4
	v_add_u32_e32 v165, 0x7000, v159
	s_waitcnt lgkmcnt(0)
	v_mfma_f32_16x16x32_bf16 v[32:35], v[166:169], v[116:119], v[32:35]
	s_add_i32 s1, s1, -1
	v_lshl_add_u64 v[154:155], v[154:155], 0, s[4:5]
	v_lshl_add_u64 v[156:157], v[156:157], 0, s[6:7]
	v_mfma_f32_16x16x32_bf16 v[20:23], v[166:169], v[120:123], v[20:23]
	ds_read2_b64 v[166:169], v164 offset0:8 offset1:12
	s_cmp_lg_u32 s1, 0
	s_waitcnt lgkmcnt(0)
	v_mfma_f32_16x16x32_bf16 v[32:35], v[166:169], v[112:115], v[32:35]
	v_mfma_f32_16x16x32_bf16 v[20:23], v[166:169], v[124:127], v[20:23]
	ds_read2_b64 v[166:169], v165 offset0:32 offset1:36
	s_waitcnt lgkmcnt(0)
	v_mfma_f32_16x16x32_bf16 v[24:27], v[166:169], v[116:119], v[24:27]
	v_mfma_f32_16x16x32_bf16 v[12:15], v[166:169], v[120:123], v[12:15]
	ds_read2_b64 v[166:169], v165 offset0:40 offset1:44
	s_waitcnt lgkmcnt(0)
	v_mfma_f32_16x16x32_bf16 v[24:27], v[166:169], v[112:115], v[24:27]
	v_mfma_f32_16x16x32_bf16 v[12:15], v[166:169], v[124:127], v[12:15]
	v_add_u32_e32 v166, 0x7800, v159
	ds_read2_b64 v[168:171], v166 offset0:64 offset1:68
	v_add_u32_e32 v167, 0x8000, v159
	s_waitcnt lgkmcnt(0)
	v_mfma_f32_16x16x32_bf16 v[16:19], v[168:171], v[116:119], v[16:19]
	v_mfma_f32_16x16x32_bf16 v[4:7], v[168:171], v[120:123], v[4:7]
	ds_read2_b64 v[168:171], v166 offset0:72 offset1:76
	s_waitcnt lgkmcnt(0)
	v_mfma_f32_16x16x32_bf16 v[16:19], v[168:171], v[112:115], v[16:19]
	v_mfma_f32_16x16x32_bf16 v[4:7], v[168:171], v[124:127], v[4:7]
	ds_read2_b64 v[168:171], v167 offset0:96 offset1:100
	s_waitcnt lgkmcnt(0)
	v_mfma_f32_16x16x32_bf16 v[8:11], v[168:171], v[116:119], v[8:11]
	ds_read2_b64 v[116:119], v167 offset0:104 offset1:108
	s_waitcnt lgkmcnt(0)
	s_barrier
	v_mfma_f32_16x16x32_bf16 v[0:3], v[168:171], v[120:123], v[0:3]
	v_mfma_f32_16x16x32_bf16 v[8:11], v[116:119], v[112:115], v[8:11]
	v_mfma_f32_16x16x32_bf16 v[0:3], v[116:119], v[124:127], v[0:3]
	s_cbranch_scc1 .LBB0_127
	s_waitcnt vmcnt(7)
	ds_write_b128 v158, v[100:103]
	s_waitcnt vmcnt(6)
	ds_write_b128 v158, v[104:107] offset:4352
	s_waitcnt vmcnt(5)
	ds_write_b128 v158, v[96:99] offset:8704
	s_waitcnt vmcnt(4)
	ds_write_b128 v158, v[88:91] offset:13056
	s_waitcnt vmcnt(3)
	ds_write_b128 v151, v[108:111] offset:17408
	s_waitcnt vmcnt(2)
	ds_write_b128 v151, v[92:95] offset:22016
	s_waitcnt vmcnt(1)
	ds_write_b128 v151, v[84:87] offset:26624
	s_waitcnt vmcnt(0)
	ds_write_b128 v151, v[80:83] offset:31232
	s_waitcnt lgkmcnt(0)
	s_barrier
	ds_read_b128 v[80:83], v147
	ds_read_b128 v[84:87], v147 offset:64
	s_movk_i32 s1, 0x4a00
	s_lshl_b32 s92, s0, 1
	s_waitcnt lgkmcnt(1)
	v_mfma_f32_16x16x32_bf16 v[80:83], v[80:83], v[76:79], 0
	ds_read_b128 v[88:91], v147 offset:192
	ds_read_b128 v[94:97], v147 offset:4416
	ds_read_b128 v[98:101], v147 offset:4544
	s_waitcnt lgkmcnt(3)
	v_mfma_f32_16x16x32_bf16 v[80:83], v[84:87], v[72:75], v[80:83]
	ds_read_b128 v[84:87], v147 offset:128
	ds_read_b128 v[102:105], v147 offset:8768
	ds_read_b128 v[106:109], v147 offset:8896
	s_waitcnt lgkmcnt(2)
	v_mfma_f32_16x16x32_bf16 v[84:87], v[84:87], v[68:71], 0
	v_mfma_f32_16x16x32_bf16 v[86:89], v[88:91], v[64:67], v[84:87]
	ds_read_b128 v[90:93], v147 offset:4352
	s_waitcnt lgkmcnt(0)
	v_mfma_f32_16x16x32_bf16 v[90:93], v[90:93], v[76:79], 0
	v_mfma_f32_16x16x32_bf16 v[90:93], v[94:97], v[72:75], v[90:93]
	ds_read_b128 v[94:97], v147 offset:4480
	s_waitcnt lgkmcnt(0)
	v_mfma_f32_16x16x32_bf16 v[94:97], v[94:97], v[68:71], 0
	v_mfma_f32_16x16x32_bf16 v[94:97], v[98:101], v[64:67], v[94:97]
	ds_read_b128 v[98:101], v147 offset:8704
	s_waitcnt lgkmcnt(0)
	v_mfma_f32_16x16x32_bf16 v[98:101], v[98:101], v[76:79], 0
	v_mfma_f32_16x16x32_bf16 v[98:101], v[102:105], v[72:75], v[98:101]
	ds_read_b128 v[102:105], v147 offset:8832
	s_waitcnt lgkmcnt(0)
	v_mfma_f32_16x16x32_bf16 v[102:105], v[102:105], v[68:71], 0
	v_mfma_f32_16x16x32_bf16 v[102:105], v[106:109], v[64:67], v[102:105]
	ds_read_b128 v[106:109], v147 offset:13056
	s_waitcnt lgkmcnt(0)
	v_mfma_f32_16x16x32_bf16 v[76:79], v[106:109], v[76:79], 0
	ds_read_b128 v[106:109], v147 offset:13120
	s_waitcnt lgkmcnt(0)
	v_mfma_f32_16x16x32_bf16 v[72:75], v[106:109], v[72:75], v[76:79]
	s_nop 4
	ds_read_b128 v[76:79], v147 offset:13184
	s_waitcnt lgkmcnt(0)
	v_mfma_f32_16x16x32_bf16 v[68:71], v[76:79], v[68:71], 0
	ds_read_b128 v[76:79], v147 offset:13248
	v_mov_b32_e32 v147, v131
	s_waitcnt lgkmcnt(0)
	v_mfma_f32_16x16x32_bf16 v[64:67], v[76:79], v[64:67], v[68:71]
	s_nop 3
	v_mul_f32_e32 v68, 0x3fb8aa3b, v80
	v_exp_f32_e32 v84, v68
	v_mul_f32_e32 v68, 0x3fb8aa3b, v81
	v_exp_f32_e32 v85, v68
	v_mul_f32_e32 v68, 0x3fb8aa3b, v82
	v_exp_f32_e32 v106, v68
	v_mul_f32_e32 v68, 0x3fb8aa3b, v83
	v_exp_f32_e32 v107, v68
	v_mul_f32_e32 v68, 0x3fb8aa3b, v90
	v_mul_f32_e32 v64, 0x3fb8aa3b, v64
	v_exp_f32_e32 v90, v68
	v_mul_f32_e32 v68, 0x3fb8aa3b, v91
	v_exp_f32_e32 v116, v64
	v_mul_f32_e32 v64, 0x3fb8aa3b, v65
	v_exp_f32_e32 v91, v68
	v_mul_f32_e32 v68, 0x3fb8aa3b, v92
	v_exp_f32_e32 v117, v64
	v_mul_f32_e32 v64, 0x3fb8aa3b, v66
	v_exp_f32_e32 v92, v68
	v_mul_f32_e32 v68, 0x3fb8aa3b, v93
	v_exp_f32_e32 v118, v64
	v_mul_f32_e32 v64, 0x3fb8aa3b, v67
	v_exp_f32_e32 v93, v68
	v_mul_f32_e32 v68, 0x3fb8aa3b, v98
	v_mul_f32_e32 v76, 0x3fb8aa3b, v86
	v_exp_f32_e32 v119, v64
	ds_read2_b64 v[64:67], v161 offset0:128 offset1:132
	v_exp_f32_e32 v98, v68
	v_mul_f32_e32 v68, 0x3fb8aa3b, v99
	v_exp_f32_e32 v112, v76
	v_mul_f32_e32 v76, 0x3fb8aa3b, v87
	v_exp_f32_e32 v99, v68
	v_mul_f32_e32 v68, 0x3fb8aa3b, v100
	v_exp_f32_e32 v113, v76
	v_mul_f32_e32 v76, 0x3fb8aa3b, v88
	v_exp_f32_e32 v100, v68
	v_mul_f32_e32 v68, 0x3fb8aa3b, v101
	v_exp_f32_e32 v114, v76
	v_mul_f32_e32 v76, 0x3fb8aa3b, v89
	v_exp_f32_e32 v101, v68
	v_mul_f32_e32 v68, 0x3fb8aa3b, v72
	v_exp_f32_e32 v115, v76
	v_mul_f32_e32 v76, 0x3fb8aa3b, v94
	ds_read2_b64 v[86:89], v161 offset0:136 offset1:140
	v_exp_f32_e32 v108, v68
	v_mul_f32_e32 v68, 0x3fb8aa3b, v73
	v_exp_f32_e32 v94, v76
	v_mul_f32_e32 v76, 0x3fb8aa3b, v95
	v_exp_f32_e32 v109, v68
	v_mul_f32_e32 v68, 0x3fb8aa3b, v74
	v_exp_f32_e32 v95, v76
	v_mul_f32_e32 v76, 0x3fb8aa3b, v96
	v_exp_f32_e32 v110, v68
	v_mul_f32_e32 v68, 0x3fb8aa3b, v75
	v_exp_f32_e32 v96, v76
	v_mul_f32_e32 v76, 0x3fb8aa3b, v97
	v_exp_f32_e32 v111, v68
	v_cvt_pk_bf16_f32 v72, v84, v85
	v_cvt_pk_bf16_f32 v73, v106, v107
	v_cvt_pk_bf16_f32 v74, v90, v91
	v_cvt_pk_bf16_f32 v75, v92, v93
	v_exp_f32_e32 v97, v76
	v_cvt_pk_bf16_f32 v68, v98, v99
	s_waitcnt lgkmcnt(1)
	v_mfma_f32_16x16x32_bf16 v[60:63], v[64:67], v[72:75], v[60:63]
	v_cvt_pk_bf16_f32 v69, v100, v101
	v_cvt_pk_bf16_f32 v70, v108, v109
	v_cvt_pk_bf16_f32 v71, v110, v111
	v_cvt_pk_bf16_f32 v80, v112, v113
	v_cvt_pk_bf16_f32 v81, v114, v115
	v_cvt_pk_bf16_f32 v82, v94, v95
	v_cvt_pk_bf16_f32 v83, v96, v97
	v_mul_f32_e32 v76, 0x3fb8aa3b, v102
	v_exp_f32_e32 v102, v76
	v_mfma_f32_16x16x32_bf16 v[64:67], v[64:67], v[80:83], v[56:59]
	v_mul_f32_e32 v76, 0x3fb8aa3b, v103
	v_exp_f32_e32 v103, v76
	v_mul_f32_e32 v76, 0x3fb8aa3b, v104
	s_waitcnt lgkmcnt(0)
	v_mfma_f32_16x16x32_bf16 v[56:59], v[86:89], v[68:71], v[60:63]
	v_exp_f32_e32 v104, v76
	v_mul_f32_e32 v76, 0x3fb8aa3b, v105
	v_exp_f32_e32 v105, v76
	ds_read2_b64 v[60:63], v160 offset0:160 offset1:164
	s_waitcnt lgkmcnt(0)
	v_mfma_f32_16x16x32_bf16 v[52:55], v[60:63], v[72:75], v[52:55]
	v_cvt_pk_bf16_f32 v76, v102, v103
	v_cvt_pk_bf16_f32 v77, v104, v105
	v_cvt_pk_bf16_f32 v78, v116, v117
	v_mfma_f32_16x16x32_bf16 v[44:47], v[60:63], v[80:83], v[44:47]
	ds_read2_b64 v[60:63], v160 offset0:168 offset1:172
	v_cvt_pk_bf16_f32 v79, v118, v119
	s_waitcnt lgkmcnt(0)
	v_mfma_f32_16x16x32_bf16 v[52:55], v[60:63], v[68:71], v[52:55]
	v_mfma_f32_16x16x32_bf16 v[60:63], v[60:63], v[76:79], v[44:47]
	s_nop 2
	ds_read2_b64 v[44:47], v162 offset0:192 offset1:196
	v_mfma_f32_16x16x32_bf16 v[64:67], v[86:89], v[76:79], v[64:67]
	ds_read2_b64 v[86:89], v162 offset0:200 offset1:204
	s_waitcnt lgkmcnt(1)
	v_mfma_f32_16x16x32_bf16 v[48:51], v[44:47], v[72:75], v[48:51]
	v_mfma_f32_16x16x32_bf16 v[36:39], v[44:47], v[80:83], v[36:39]
	s_waitcnt lgkmcnt(0)
	v_mfma_f32_16x16x32_bf16 v[44:47], v[86:89], v[68:71], v[48:51]
	v_mfma_f32_16x16x32_bf16 v[48:51], v[86:89], v[76:79], v[36:39]
	ds_read2_b64 v[86:89], v163 offset0:232 offset1:236
	s_nop 3
	ds_read2_b64 v[36:39], v163 offset0:224 offset1:228
	s_waitcnt lgkmcnt(0)
	v_mfma_f32_16x16x32_bf16 v[40:43], v[36:39], v[72:75], v[40:43]
	v_mfma_f32_16x16x32_bf16 v[28:31], v[36:39], v[80:83], v[28:31]
	v_mfma_f32_16x16x32_bf16 v[36:39], v[86:89], v[68:71], v[40:43]
	v_mfma_f32_16x16x32_bf16 v[40:43], v[86:89], v[76:79], v[28:31]
	ds_read2_b64 v[86:89], v164 offset0:8 offset1:12
	s_nop 4
	ds_read2_b64 v[28:31], v164 offset1:4
	s_waitcnt lgkmcnt(0)
	v_mfma_f32_16x16x32_bf16 v[32:35], v[28:31], v[72:75], v[32:35]
	v_mfma_f32_16x16x32_bf16 v[20:23], v[28:31], v[80:83], v[20:23]
	v_mfma_f32_16x16x32_bf16 v[28:31], v[86:89], v[68:71], v[32:35]
	v_mfma_f32_16x16x32_bf16 v[32:35], v[86:89], v[76:79], v[20:23]
	ds_read2_b64 v[86:89], v165 offset0:40 offset1:44
	s_nop 4
	ds_read2_b64 v[20:23], v165 offset0:32 offset1:36
	s_waitcnt lgkmcnt(0)
	v_mfma_f32_16x16x32_bf16 v[24:27], v[20:23], v[72:75], v[24:27]
	v_mfma_f32_16x16x32_bf16 v[20:23], v[20:23], v[80:83], v[12:15]
	v_mfma_f32_16x16x32_bf16 v[12:15], v[86:89], v[68:71], v[24:27]
	s_nop 5
	ds_read2_b64 v[24:27], v166 offset0:64 offset1:68
	v_mfma_f32_16x16x32_bf16 v[20:23], v[86:89], v[76:79], v[20:23]
	ds_read2_b64 v[86:89], v166 offset0:72 offset1:76
	s_waitcnt lgkmcnt(1)
	v_mfma_f32_16x16x32_bf16 v[16:19], v[24:27], v[72:75], v[16:19]
	v_mfma_f32_16x16x32_bf16 v[24:27], v[24:27], v[80:83], v[4:7]
	s_waitcnt lgkmcnt(0)
	v_mfma_f32_16x16x32_bf16 v[4:7], v[86:89], v[68:71], v[16:19]
	v_mfma_f32_16x16x32_bf16 v[16:19], v[86:89], v[76:79], v[24:27]
	s_nop 4
	ds_read2_b64 v[24:27], v167 offset0:96 offset1:100
	s_waitcnt lgkmcnt(0)
	v_mfma_f32_16x16x32_bf16 v[8:11], v[24:27], v[72:75], v[8:11]
	v_mfma_f32_16x16x32_bf16 v[0:3], v[24:27], v[80:83], v[0:3]
	ds_read2_b64 v[24:27], v167 offset0:104 offset1:108
	s_waitcnt lgkmcnt(0)
	s_barrier
	v_mfma_f32_16x16x32_bf16 v[72:75], v[24:27], v[68:71], v[8:11]
	s_nop 2
	v_and_b32_e32 v9, 64, v205
	v_add_u32_e32 v9, 64, v9
	v_mfma_f32_16x16x32_bf16 v[24:27], v[24:27], v[76:79], v[0:3]
	global_load_dword v8, v131, s[10:11] offset:16
	s_nop 1
	global_load_dword v0, v131, s[10:11]
	v_add_f32_e32 v2, 0, v84
	v_add_f32_e32 v2, v85, v2
	v_add_f32_e32 v2, v106, v2
	v_add_f32_e32 v2, v107, v2
	v_add_f32_e32 v2, v2, v90
	v_add_f32_e32 v2, v91, v2
	v_add_f32_e32 v2, v92, v2
	v_add_f32_e32 v2, v93, v2
	v_add_f32_e32 v2, v2, v98
	v_add_f32_e32 v2, v99, v2
	v_add_f32_e32 v2, v100, v2
	v_add_f32_e32 v2, v101, v2
	v_add_f32_e32 v2, v2, v108
	v_add_f32_e32 v2, v109, v2
	v_xor_b32_e32 v3, 16, v205
	v_add_f32_e32 v1, 0, v112
	v_add_f32_e32 v2, v110, v2
	v_cmp_lt_i32_e32 vcc, v3, v9
	v_add_f32_e32 v1, v113, v1
	v_add_f32_e32 v2, v111, v2
	v_cndmask_b32_e32 v3, v205, v3, vcc
	v_add_f32_e32 v1, v114, v1
	v_add_f32_e32 v2, v152, v2
	v_lshlrev_b32_e32 v69, 2, v3
	v_add_f32_e32 v1, v115, v1
	ds_bpermute_b32 v3, v69, v2
	v_add_f32_e32 v1, v1, v94
	v_add_f32_e32 v1, v95, v1
	v_add_f32_e32 v1, v96, v1
	v_add_f32_e32 v1, v97, v1
	v_add_f32_e32 v1, v1, v102
	s_waitcnt lgkmcnt(0)
	v_add_f32_e32 v2, v2, v3
	v_xor_b32_e32 v3, 32, v205
	v_add_f32_e32 v1, v103, v1
	v_cmp_lt_i32_e32 vcc, v3, v9
	v_add_f32_e32 v1, v104, v1
	v_add_f32_e32 v1, v105, v1
	v_cndmask_b32_e32 v3, v205, v3, vcc
	v_lshlrev_b32_e32 v71, 2, v3
	v_add_f32_e32 v1, v1, v116
	ds_bpermute_b32 v3, v71, v2
	v_add_f32_e32 v1, v117, v1
	v_add_f32_e32 v1, v118, v1
	v_add_f32_e32 v1, v119, v1
	v_add_f32_e32 v1, v153, v1
	s_waitcnt lgkmcnt(0)
	v_add_f32_e32 v2, v2, v3
	ds_bpermute_b32 v3, v69, v1
	s_waitcnt lgkmcnt(0)
	v_add_f32_e32 v1, v1, v3
	ds_bpermute_b32 v3, v71, v1
	s_waitcnt lgkmcnt(0)
	v_add_f32_e32 v1, v1, v3
	v_div_scale_f32 v3, s[26:27], v2, v2, 1.0
	v_rcp_f32_e32 v9, v3
	s_nop 0
	v_fma_f32 v10, -v3, v9, 1.0
	v_fmac_f32_e32 v9, v10, v9
	v_div_scale_f32 v10, vcc, 1.0, v2, 1.0
	v_mul_f32_e32 v11, v10, v9
	v_fma_f32 v68, -v3, v11, v10
	v_fmac_f32_e32 v11, v68, v9
	v_fma_f32 v3, -v3, v11, v10
	v_div_fmas_f32 v3, v3, v9, v11
	v_div_fixup_f32 v68, v3, v2, 1.0
	s_waitcnt vmcnt(0)
	v_div_scale_f32 v2, s[26:27], v1, v1, v0
	v_rcp_f32_e32 v3, v2
	s_nop 0
	v_fma_f32 v9, -v2, v3, 1.0
	v_fmac_f32_e32 v3, v9, v3
	v_div_scale_f32 v9, vcc, v0, v1, v0
	v_mul_f32_e32 v10, v9, v3
	v_fma_f32 v11, -v2, v10, v9
	v_fmac_f32_e32 v10, v11, v3
	v_fma_f32 v2, -v2, v10, v9
	v_div_fmas_f32 v2, v2, v3, v10
	v_div_fixup_f32 v70, v2, v1, v0
	v_pk_mul_f32 v[0:1], v[18:19], v[70:71] op_sel_hi:[1,0]
	v_pk_mul_f32 v[64:65], v[64:65], v[70:71] op_sel_hi:[1,0]
	v_pk_fma_f32 v[10:11], v[6:7], v[68:69], v[0:1] op_sel_hi:[1,0,1] neg_lo:[0,0,1] neg_hi:[0,0,1]
	v_mov_b64_e32 v[6:7], s[96:97]
	v_mad_i64_i32 v[6:7], s[26:27], v150, s1, v[6:7]
	v_readlane_b32 s0, v254, 47
	v_pk_mul_f32 v[0:1], v[24:25], v[70:71] op_sel_hi:[1,0]
	v_lshl_add_u64 v[6:7], v[6:7], 0, s[92:93]
	v_readlane_b32 s1, v254, 48
	v_pk_fma_f32 v[2:3], v[72:73], v[68:69], v[0:1] op_sel_hi:[1,0,1] neg_lo:[0,0,1] neg_hi:[0,0,1]
	v_sub_f32_e32 v72, 1.0, v8
	v_lshl_add_u64 v[8:9], v[148:149], 1, s[0:1]
	v_lshl_add_u64 v[6:7], v[6:7], 0, v[146:147]
	s_mov_b64 s[0:1], 0x92a8f00
	v_lshl_add_u64 v[78:79], v[8:9], 0, s[92:93]
	v_lshl_add_u64 v[8:9], v[6:7], 0, s[0:1]
	s_mov_b32 s0, 0x92a8000
	v_add_co_u32_e32 v6, vcc, s0, v6
	v_pk_mul_f32 v[0:1], v[26:27], v[70:71] op_sel_hi:[1,0]
	s_nop 0
	v_addc_co_u32_e32 v7, vcc, 0, v7, vcc
	global_load_dwordx2 v[6:7], v[6:7], off offset:3840
	v_pk_fma_f32 v[0:1], v[74:75], v[68:69], v[0:1] op_sel_hi:[1,0,1] neg_lo:[0,0,1] neg_hi:[0,0,1]
	global_load_dwordx4 v[74:77], v130, s[12:13]
	v_pk_mul_f32 v[66:67], v[66:67], v[70:71] op_sel_hi:[1,0]
	v_pk_fma_f32 v[56:57], v[56:57], v[68:69], v[64:65] op_sel_hi:[1,0,1] neg_lo:[0,0,1] neg_hi:[0,0,1]
	v_pk_fma_f32 v[58:59], v[58:59], v[68:69], v[66:67] op_sel_hi:[1,0,1] neg_lo:[0,0,1] neg_hi:[0,0,1]
	v_pk_mul_f32 v[64:65], v[56:57], v[56:57]
	v_pk_mul_f32 v[66:67], v[58:59], v[58:59]
	v_pk_mul_f32 v[60:61], v[60:61], v[70:71] op_sel_hi:[1,0]
	v_add_f32_e32 v64, v64, v65
	v_pk_fma_f32 v[52:53], v[52:53], v[68:69], v[60:61] op_sel_hi:[1,0,1] neg_lo:[0,0,1] neg_hi:[0,0,1]
	v_add_f32_e32 v64, v66, v64
	v_pk_mul_f32 v[62:63], v[62:63], v[70:71] op_sel_hi:[1,0]
	v_pk_mul_f32 v[60:61], v[52:53], v[52:53]
	v_add_f32_e32 v64, v67, v64
	v_pk_fma_f32 v[54:55], v[54:55], v[68:69], v[62:63] op_sel_hi:[1,0,1] neg_lo:[0,0,1] neg_hi:[0,0,1]
	v_add_f32_e32 v60, v60, v64
	v_pk_mul_f32 v[62:63], v[54:55], v[54:55]
	v_pk_mul_f32 v[48:49], v[48:49], v[70:71] op_sel_hi:[1,0]
	v_add_f32_e32 v60, v61, v60
	v_pk_fma_f32 v[44:45], v[44:45], v[68:69], v[48:49] op_sel_hi:[1,0,1] neg_lo:[0,0,1] neg_hi:[0,0,1]
	v_add_f32_e32 v60, v62, v60
	v_pk_mul_f32 v[50:51], v[50:51], v[70:71] op_sel_hi:[1,0]
	v_pk_mul_f32 v[48:49], v[44:45], v[44:45]
	v_add_f32_e32 v60, v63, v60
	v_pk_fma_f32 v[46:47], v[46:47], v[68:69], v[50:51] op_sel_hi:[1,0,1] neg_lo:[0,0,1] neg_hi:[0,0,1]
	v_add_f32_e32 v48, v48, v60
	v_pk_mul_f32 v[50:51], v[46:47], v[46:47]
	v_pk_mul_f32 v[40:41], v[40:41], v[70:71] op_sel_hi:[1,0]
	v_add_f32_e32 v48, v49, v48
	v_pk_fma_f32 v[36:37], v[36:37], v[68:69], v[40:41] op_sel_hi:[1,0,1] neg_lo:[0,0,1] neg_hi:[0,0,1]
	v_add_f32_e32 v48, v50, v48
	v_pk_mul_f32 v[42:43], v[42:43], v[70:71] op_sel_hi:[1,0]
	v_pk_mul_f32 v[40:41], v[36:37], v[36:37]
	v_add_f32_e32 v48, v51, v48
	v_pk_fma_f32 v[38:39], v[38:39], v[68:69], v[42:43] op_sel_hi:[1,0,1] neg_lo:[0,0,1] neg_hi:[0,0,1]
	v_add_f32_e32 v40, v40, v48
	v_pk_mul_f32 v[42:43], v[38:39], v[38:39]
	v_pk_mul_f32 v[32:33], v[32:33], v[70:71] op_sel_hi:[1,0]
	v_add_f32_e32 v40, v41, v40
	v_pk_fma_f32 v[28:29], v[28:29], v[68:69], v[32:33] op_sel_hi:[1,0,1] neg_lo:[0,0,1] neg_hi:[0,0,1]
	v_add_f32_e32 v40, v42, v40
	v_pk_mul_f32 v[34:35], v[34:35], v[70:71] op_sel_hi:[1,0]
	v_pk_mul_f32 v[32:33], v[28:29], v[28:29]
	v_add_f32_e32 v40, v43, v40
	v_pk_fma_f32 v[30:31], v[30:31], v[68:69], v[34:35] op_sel_hi:[1,0,1] neg_lo:[0,0,1] neg_hi:[0,0,1]
	v_add_f32_e32 v32, v32, v40
	v_pk_mul_f32 v[34:35], v[30:31], v[30:31]
	v_pk_mul_f32 v[20:21], v[20:21], v[70:71] op_sel_hi:[1,0]
	v_add_f32_e32 v32, v33, v32
	v_pk_fma_f32 v[20:21], v[12:13], v[68:69], v[20:21] op_sel_hi:[1,0,1] neg_lo:[0,0,1] neg_hi:[0,0,1]
	v_add_f32_e32 v32, v34, v32
	v_pk_mul_f32 v[22:23], v[22:23], v[70:71] op_sel_hi:[1,0]
	v_pk_mul_f32 v[12:13], v[20:21], v[20:21]
	v_add_f32_e32 v32, v35, v32
	v_pk_fma_f32 v[22:23], v[14:15], v[68:69], v[22:23] op_sel_hi:[1,0,1] neg_lo:[0,0,1] neg_hi:[0,0,1]
	v_add_f32_e32 v12, v12, v32
	v_pk_mul_f32 v[14:15], v[22:23], v[22:23]
	v_pk_mul_f32 v[16:17], v[16:17], v[70:71] op_sel_hi:[1,0]
	v_add_f32_e32 v12, v13, v12
	v_pk_fma_f32 v[16:17], v[4:5], v[68:69], v[16:17] op_sel_hi:[1,0,1] neg_lo:[0,0,1] neg_hi:[0,0,1]
	v_add_f32_e32 v12, v14, v12
	v_pk_mul_f32 v[4:5], v[16:17], v[16:17]
	v_add_f32_e32 v12, v15, v12
	v_add_f32_e32 v4, v4, v12
	v_pk_mul_f32 v[18:19], v[10:11], v[10:11]
	v_add_f32_e32 v4, v5, v4
	v_add_f32_e32 v4, v18, v4
	v_pk_mul_f32 v[24:25], v[2:3], v[2:3]
	v_add_f32_e32 v4, v19, v4
	v_add_f32_e32 v4, v24, v4
	v_pk_mul_f32 v[26:27], v[0:1], v[0:1]
	v_add_f32_e32 v4, v25, v4
	v_add_f32_e32 v4, v26, v4
	v_add_f32_e32 v4, v27, v4
	ds_bpermute_b32 v5, v69, v4
	s_waitcnt vmcnt(1)
	v_lshlrev_b32_e32 v80, 16, v6
	v_mul_f32_e32 v73, 0xbfb8aa3b, v80
	v_exp_f32_e32 v73, v73
	v_and_b32_e32 v81, 0xffff0000, v6
	v_lshlrev_b32_e32 v6, 16, v7
	v_and_b32_e32 v7, 0xffff0000, v7
	v_add_f32_e32 v73, 1.0, v73
	v_rcp_f32_e32 v82, v73
	v_mul_f32_e32 v73, 0xbfb8aa3b, v81
	v_exp_f32_e32 v73, v73
	s_waitcnt lgkmcnt(0)
	v_add_f32_e32 v4, v4, v5
	ds_bpermute_b32 v5, v71, v4
	v_add_f32_e32 v73, 1.0, v73
	v_rcp_f32_e32 v83, v73
	v_mul_f32_e32 v73, 0xbfb8aa3b, v6
	v_exp_f32_e32 v73, v73
	s_waitcnt lgkmcnt(0)
	v_add_f32_e32 v4, v4, v5
	v_pk_mul_f32 v[80:81], v[82:83], v[80:81]
	v_fmamk_f32 v4, v4, 0x3c000000, v210
	v_add_f32_e32 v73, 1.0, v73
	v_rcp_f32_e32 v82, v73
	v_mul_f32_e32 v73, 0xbfb8aa3b, v7
	v_exp_f32_e32 v73, v73
	v_rsq_f32_e32 v4, v4
	v_add_f32_e32 v73, 1.0, v73
	v_rcp_f32_e32 v83, v73
	v_mul_f32_e32 v4, v72, v4
	v_pk_mul_f32 v[12:13], v[56:57], v[4:5] op_sel_hi:[1,0]
	v_pk_mul_f32 v[14:15], v[58:59], v[4:5] op_sel_hi:[1,0]
	v_pk_mul_f32 v[82:83], v[82:83], v[6:7]
	v_lshl_add_u64 v[6:7], v[78:79], 0, v[146:147]
	global_load_dwordx2 v[78:79], v[8:9], off offset:32
	s_waitcnt vmcnt(1)
	v_pk_mul_f32 v[12:13], v[74:75], v[12:13]
	v_pk_mul_f32 v[14:15], v[76:77], v[14:15]
	v_pk_mul_f32 v[12:13], v[80:81], v[12:13]
	v_pk_mul_f32 v[14:15], v[82:83], v[14:15]
	v_cvt_pk_bf16_f32 v12, v12, v13
	v_cvt_pk_bf16_f32 v13, v14, v15
	global_store_dwordx2 v[6:7], v[12:13], off
	global_load_dwordx4 v[12:15], v130, s[12:13] offset:64
	v_pk_mul_f32 v[18:19], v[52:53], v[4:5] op_sel_hi:[1,0]
	s_waitcnt vmcnt(2)
	v_lshlrev_b32_e32 v84, 16, v78
	v_mul_f32_e32 v73, 0xbfb8aa3b, v84
	v_exp_f32_e32 v73, v73
	v_and_b32_e32 v85, 0xffff0000, v78
	v_lshlrev_b32_e32 v78, 16, v79
	v_and_b32_e32 v79, 0xffff0000, v79
	v_add_f32_e32 v73, 1.0, v73
	v_rcp_f32_e32 v86, v73
	v_mul_f32_e32 v73, 0xbfb8aa3b, v85
	v_exp_f32_e32 v73, v73
	s_waitcnt vmcnt(0)
	v_pk_mul_f32 v[12:13], v[12:13], v[18:19]
	v_pk_mul_f32 v[18:19], v[54:55], v[4:5] op_sel_hi:[1,0]
	v_add_f32_e32 v73, 1.0, v73
	v_rcp_f32_e32 v87, v73
	v_mul_f32_e32 v73, 0xbfb8aa3b, v78
	v_exp_f32_e32 v73, v73
	v_pk_mul_f32 v[14:15], v[14:15], v[18:19]
	v_pk_mul_f32 v[84:85], v[86:87], v[84:85]
	v_pk_mul_f32 v[18:19], v[44:45], v[4:5] op_sel_hi:[1,0]
	v_add_f32_e32 v73, 1.0, v73
	v_rcp_f32_e32 v86, v73
	v_mul_f32_e32 v73, 0xbfb8aa3b, v79
	v_exp_f32_e32 v73, v73
	v_pk_mul_f32 v[12:13], v[84:85], v[12:13]
	v_add_f32_e32 v73, 1.0, v73
	v_rcp_f32_e32 v87, v73
	v_cvt_pk_bf16_f32 v12, v12, v13
	v_pk_mul_f32 v[78:79], v[86:87], v[78:79]
	global_load_dwordx2 v[86:87], v[8:9], off offset:64
	v_pk_mul_f32 v[14:15], v[78:79], v[14:15]
	s_waitcnt vmcnt(0)
	v_lshlrev_b32_e32 v88, 16, v86
	v_mul_f32_e32 v73, 0xbfb8aa3b, v88
	v_exp_f32_e32 v73, v73
	v_and_b32_e32 v89, 0xffff0000, v86
	v_lshlrev_b32_e32 v86, 16, v87
	v_and_b32_e32 v87, 0xffff0000, v87
	v_add_f32_e32 v73, 1.0, v73
	v_rcp_f32_e32 v90, v73
	v_mul_f32_e32 v73, 0xbfb8aa3b, v89
	v_exp_f32_e32 v73, v73
	v_cvt_pk_bf16_f32 v13, v14, v15
	global_store_dwordx2 v[6:7], v[12:13], off offset:32
	global_load_dwordx4 v[12:15], v130, s[12:13] offset:128
	v_add_f32_e32 v73, 1.0, v73
	v_rcp_f32_e32 v91, v73
	v_mul_f32_e32 v73, 0xbfb8aa3b, v86
	v_exp_f32_e32 v73, v73
	v_pk_mul_f32 v[88:89], v[90:91], v[88:89]
	v_add_f32_e32 v73, 1.0, v73
	v_rcp_f32_e32 v90, v73
	v_mul_f32_e32 v73, 0xbfb8aa3b, v87
	v_exp_f32_e32 v73, v73
	s_waitcnt vmcnt(0)
	v_pk_mul_f32 v[12:13], v[12:13], v[18:19]
	v_add_f32_e32 v73, 1.0, v73
	v_rcp_f32_e32 v91, v73
	v_pk_mul_f32 v[18:19], v[46:47], v[4:5] op_sel_hi:[1,0]
	v_pk_mul_f32 v[12:13], v[88:89], v[12:13]
	v_pk_mul_f32 v[14:15], v[14:15], v[18:19]
	v_pk_mul_f32 v[86:87], v[90:91], v[86:87]
	global_load_dwordx2 v[90:91], v[8:9], off offset:96
	v_pk_mul_f32 v[14:15], v[86:87], v[14:15]
	v_cvt_pk_bf16_f32 v12, v12, v13
	v_cvt_pk_bf16_f32 v13, v14, v15
	global_store_dwordx2 v[6:7], v[12:13], off offset:64
	global_load_dwordx4 v[12:15], v130, s[12:13] offset:192
	v_pk_mul_f32 v[18:19], v[36:37], v[4:5] op_sel_hi:[1,0]
	s_waitcnt vmcnt(2)
	v_lshlrev_b32_e32 v92, 16, v90
	v_mul_f32_e32 v73, 0xbfb8aa3b, v92
	v_exp_f32_e32 v73, v73
	v_and_b32_e32 v93, 0xffff0000, v90
	v_lshlrev_b32_e32 v90, 16, v91
	v_and_b32_e32 v91, 0xffff0000, v91
	v_add_f32_e32 v73, 1.0, v73
	v_rcp_f32_e32 v94, v73
	v_mul_f32_e32 v73, 0xbfb8aa3b, v93
	v_exp_f32_e32 v73, v73
	s_waitcnt vmcnt(0)
	v_pk_mul_f32 v[12:13], v[12:13], v[18:19]
	v_pk_mul_f32 v[18:19], v[38:39], v[4:5] op_sel_hi:[1,0]
	v_add_f32_e32 v73, 1.0, v73
	v_rcp_f32_e32 v95, v73
	v_mul_f32_e32 v73, 0xbfb8aa3b, v90
	v_exp_f32_e32 v73, v73
	v_pk_mul_f32 v[14:15], v[14:15], v[18:19]
	v_pk_mul_f32 v[92:93], v[94:95], v[92:93]
	v_pk_mul_f32 v[18:19], v[28:29], v[4:5] op_sel_hi:[1,0]
	v_add_f32_e32 v73, 1.0, v73
	v_rcp_f32_e32 v94, v73
	v_mul_f32_e32 v73, 0xbfb8aa3b, v91
	v_exp_f32_e32 v73, v73
	v_pk_mul_f32 v[12:13], v[92:93], v[12:13]
	v_add_f32_e32 v73, 1.0, v73
	v_rcp_f32_e32 v95, v73
	v_cvt_pk_bf16_f32 v12, v12, v13
	v_pk_mul_f32 v[90:91], v[94:95], v[90:91]
	global_load_dwordx2 v[94:95], v[8:9], off offset:128
	v_pk_mul_f32 v[14:15], v[90:91], v[14:15]
	s_waitcnt vmcnt(0)
	v_lshlrev_b32_e32 v96, 16, v94
	v_cvt_pk_bf16_f32 v13, v14, v15
	global_store_dwordx2 v[6:7], v[12:13], off offset:96
	global_load_dwordx4 v[12:15], v130, s[12:13] offset:256
	v_mul_f32_e32 v73, 0xbfb8aa3b, v96
	v_exp_f32_e32 v73, v73
	v_and_b32_e32 v97, 0xffff0000, v94
	v_lshlrev_b32_e32 v94, 16, v95
	v_and_b32_e32 v95, 0xffff0000, v95
	v_add_f32_e32 v73, 1.0, v73
	v_rcp_f32_e32 v98, v73
	v_mul_f32_e32 v73, 0xbfb8aa3b, v97
	v_exp_f32_e32 v73, v73
	s_waitcnt vmcnt(0)
	v_pk_mul_f32 v[12:13], v[12:13], v[18:19]
	v_add_f32_e32 v73, 1.0, v73
	v_rcp_f32_e32 v99, v73
	v_mul_f32_e32 v73, 0xbfb8aa3b, v94
	v_exp_f32_e32 v73, v73
	v_pk_mul_f32 v[18:19], v[30:31], v[4:5] op_sel_hi:[1,0]
	v_pk_mul_f32 v[96:97], v[98:99], v[96:97]
	v_pk_mul_f32 v[14:15], v[14:15], v[18:19]
	v_add_f32_e32 v73, 1.0, v73
	v_rcp_f32_e32 v98, v73
	v_mul_f32_e32 v73, 0xbfb8aa3b, v95
	v_exp_f32_e32 v73, v73
	v_pk_mul_f32 v[12:13], v[96:97], v[12:13]
	v_pk_mul_f32 v[18:19], v[20:21], v[4:5] op_sel_hi:[1,0]
	v_cvt_pk_bf16_f32 v12, v12, v13
	v_add_f32_e32 v73, 1.0, v73
	v_rcp_f32_e32 v99, v73
	s_nop 0
	v_pk_mul_f32 v[94:95], v[98:99], v[94:95]
	global_load_dwordx2 v[98:99], v[8:9], off offset:160
	v_pk_mul_f32 v[14:15], v[94:95], v[14:15]
	s_waitcnt vmcnt(0)
	v_lshlrev_b32_e32 v100, 16, v98
	v_cvt_pk_bf16_f32 v13, v14, v15
	global_store_dwordx2 v[6:7], v[12:13], off offset:128
	global_load_dwordx4 v[12:15], v130, s[12:13] offset:320
	v_mul_f32_e32 v73, 0xbfb8aa3b, v100
	v_exp_f32_e32 v73, v73
	v_and_b32_e32 v101, 0xffff0000, v98
	v_lshlrev_b32_e32 v98, 16, v99
	v_and_b32_e32 v99, 0xffff0000, v99
	v_add_f32_e32 v73, 1.0, v73
	v_rcp_f32_e32 v102, v73
	v_mul_f32_e32 v73, 0xbfb8aa3b, v101
	v_exp_f32_e32 v73, v73
	s_waitcnt vmcnt(0)
	v_pk_mul_f32 v[12:13], v[18:19], v[12:13]
	v_add_f32_e32 v73, 1.0, v73
	v_rcp_f32_e32 v103, v73
	v_mul_f32_e32 v73, 0xbfb8aa3b, v98
	v_exp_f32_e32 v73, v73
	v_pk_mul_f32 v[18:19], v[22:23], v[4:5] op_sel_hi:[1,0]
	v_pk_mul_f32 v[100:101], v[102:103], v[100:101]
	v_pk_mul_f32 v[14:15], v[18:19], v[14:15]
	v_add_f32_e32 v73, 1.0, v73
	v_rcp_f32_e32 v102, v73
	v_mul_f32_e32 v73, 0xbfb8aa3b, v99
	v_exp_f32_e32 v73, v73
	v_pk_mul_f32 v[12:13], v[12:13], v[100:101]
	v_add_f32_e32 v73, 1.0, v73
	v_rcp_f32_e32 v103, v73
	v_cvt_pk_bf16_f32 v12, v12, v13
	v_pk_mul_f32 v[98:99], v[102:103], v[98:99]
	s_nop 0
	v_pk_mul_f32 v[14:15], v[14:15], v[98:99]
	s_nop 0
	v_cvt_pk_bf16_f32 v13, v14, v15
	global_store_dwordx2 v[6:7], v[12:13], off offset:160
	global_load_dwordx2 v[18:19], v[8:9], off offset:192
	s_nop 0
	global_load_dwordx4 v[12:15], v130, s[12:13] offset:384
	s_waitcnt vmcnt(1)
	v_lshlrev_b32_e32 v20, 16, v18
	v_mul_f32_e32 v5, 0xbfb8aa3b, v20
	v_exp_f32_e32 v5, v5
	v_and_b32_e32 v21, 0xffff0000, v18
	global_load_dwordx2 v[8:9], v[8:9], off offset:224
	v_add_f32_e32 v5, 1.0, v5
	v_rcp_f32_e32 v22, v5
	v_pk_mul_f32 v[16:17], v[16:17], v[4:5] op_sel_hi:[1,0]
	v_mul_f32_e32 v5, 0xbfb8aa3b, v21
	v_exp_f32_e32 v5, v5
	s_waitcnt vmcnt(1)
	v_pk_mul_f32 v[12:13], v[16:17], v[12:13]
	v_add_f32_e32 v5, 1.0, v5
	v_rcp_f32_e32 v23, v5
	s_nop 0
	v_pk_mul_f32 v[16:17], v[22:23], v[20:21]
	s_nop 0
	v_pk_mul_f32 v[12:13], v[12:13], v[16:17]
	v_lshlrev_b32_e32 v16, 16, v19
	v_mul_f32_e32 v5, 0xbfb8aa3b, v16
	v_exp_f32_e32 v5, v5
	v_and_b32_e32 v17, 0xffff0000, v19
	v_cvt_pk_bf16_f32 v12, v12, v13
	v_add_f32_e32 v5, 1.0, v5
	v_rcp_f32_e32 v18, v5
	v_pk_mul_f32 v[10:11], v[10:11], v[4:5] op_sel_hi:[1,0]
	v_mul_f32_e32 v5, 0xbfb8aa3b, v17
	v_exp_f32_e32 v5, v5
	v_pk_mul_f32 v[10:11], v[10:11], v[14:15]
	v_add_f32_e32 v5, 1.0, v5
	v_rcp_f32_e32 v19, v5
	s_nop 0
	v_pk_mul_f32 v[14:15], v[18:19], v[16:17]
	s_nop 0
	v_pk_mul_f32 v[10:11], v[10:11], v[14:15]
	s_nop 0
	v_cvt_pk_bf16_f32 v13, v10, v11
	global_store_dwordx2 v[6:7], v[12:13], off offset:192
	global_load_dwordx4 v[12:15], v130, s[12:13] offset:448
	s_waitcnt vmcnt(2)
	v_lshlrev_b32_e32 v10, 16, v8
	v_mul_f32_e32 v5, 0xbfb8aa3b, v10
	v_exp_f32_e32 v5, v5
	v_and_b32_e32 v11, 0xffff0000, v8
	v_lshlrev_b32_e32 v8, 16, v9
	v_and_b32_e32 v9, 0xffff0000, v9
	v_add_f32_e32 v5, 1.0, v5
	v_rcp_f32_e32 v16, v5
	v_pk_mul_f32 v[2:3], v[2:3], v[4:5] op_sel_hi:[1,0]
	v_mul_f32_e32 v5, 0xbfb8aa3b, v11
	v_exp_f32_e32 v5, v5
	s_waitcnt vmcnt(0)
	v_pk_mul_f32 v[2:3], v[2:3], v[12:13]
	v_add_f32_e32 v5, 1.0, v5
	v_rcp_f32_e32 v17, v5
	v_mul_f32_e32 v5, 0xbfb8aa3b, v8
	v_exp_f32_e32 v5, v5
	v_pk_mul_f32 v[10:11], v[16:17], v[10:11]
	s_nop 0
	v_pk_mul_f32 v[2:3], v[2:3], v[10:11]
	v_add_f32_e32 v5, 1.0, v5
	v_pk_mul_f32 v[0:1], v[0:1], v[4:5] op_sel_hi:[1,0]
	v_mul_f32_e32 v4, 0xbfb8aa3b, v9
	v_exp_f32_e32 v4, v4
	v_rcp_f32_e32 v10, v5
	v_pk_mul_f32 v[0:1], v[0:1], v[14:15]
	v_cvt_pk_bf16_f32 v2, v2, v3
	v_add_f32_e32 v4, 1.0, v4
	v_rcp_f32_e32 v11, v4
	s_nop 0
	v_pk_mul_f32 v[4:5], v[10:11], v[8:9]
	s_nop 0
	v_pk_mul_f32 v[0:1], v[0:1], v[4:5]
	s_nop 0
	v_cvt_pk_bf16_f32 v3, v0, v1
	global_store_dwordx2 v[6:7], v[2:3], off offset:224
